# v22: v21 plus nt stores for the converted weight images (used several phases later)
# speedup vs baseline: 1.0642x; 1.0020x over previous
.LBB0_8:
	s_or_b64 exec, exec, s[44:45]
	s_waitcnt vmcnt(0)
	ds_write2_b32 v46, v2, v3 offset1:1
	ds_write2_b32 v46, v4, v5 offset0:2 offset1:3
	v_add_u32_e32 v2, 0x420, v46
	ds_write2_b32 v2, v10, v11 offset1:1
	v_add_u32_e32 v2, 0x428, v46
	ds_write2_b32 v2, v12, v13 offset1:1
	v_add_u32_e32 v2, 0x840, v46
	ds_write2_b32 v2, v6, v7 offset1:1
	v_add_u32_e32 v2, 0x848, v46
	ds_write2_b32 v2, v8, v9 offset1:1
	v_add_u32_e32 v2, 0xc60, v46
	ds_write2_b32 v2, v18, v19 offset1:1
	v_add_u32_e32 v2, 0xc68, v46
	ds_write2_b32 v2, v20, v21 offset1:1
	v_add_u32_e32 v2, 0x1080, v46
	ds_write2_b32 v2, v14, v15 offset1:1
	v_add_u32_e32 v2, 0x1088, v46
	ds_write2_b32 v2, v16, v17 offset1:1
	v_add_u32_e32 v2, 0x14a0, v46
	ds_write2_b32 v2, v26, v27 offset1:1
	v_add_u32_e32 v2, 0x14a8, v46
	ds_write2_b32 v2, v28, v29 offset1:1
	v_add_u32_e32 v2, 0x18c0, v46
	ds_write2_b32 v2, v22, v23 offset1:1
	v_add_u32_e32 v2, 0x18c8, v46
	ds_write2_b32 v2, v24, v25 offset1:1
	v_add_u32_e32 v2, 0x1ce0, v46
	ds_write2_b32 v2, v30, v31 offset1:1
	v_add_u32_e32 v2, 0x1ce8, v46
	ds_write2_b32 v2, v32, v33 offset1:1
	s_waitcnt lgkmcnt(0)
	ds_read_b32 v2, v45
	ds_read_b32 v3, v45 offset:132
	ds_read_b32 v4, v45 offset:264
	ds_read_b32 v5, v45 offset:396
	ds_read_b32 v8, v45 offset:528
	ds_read_b32 v9, v45 offset:660
	ds_read_b32 v10, v45 offset:792
	ds_read_b32 v11, v45 offset:924
	s_waitcnt lgkmcnt(0)
	v_cvt_pk_bf16_f32 v2, v2, v3
	s_waitcnt lgkmcnt(4)
	v_cvt_pk_bf16_f32 v3, v4, v5
	s_waitcnt lgkmcnt(2)
	v_cvt_pk_bf16_f32 v4, v8, v9
	v_add_u32_e32 v8, s40, v43
	s_ashr_i32 s43, s42, 31
	v_ashrrev_i32_e32 v9, 31, v8
	v_lshl_add_u64 v[6:7], s[42:43], 1, v[38:39]
	s_waitcnt lgkmcnt(0)
	v_cvt_pk_bf16_f32 v5, v10, v11
	v_lshlrev_b64 v[10:11], 11, v[8:9]
	v_lshl_add_u64 v[10:11], v[6:7], 0, v[10:11]
	global_store_dwordx4 v[10:11], v[2:5], off nt
	ds_read_b32 v2, v45 offset:32
	ds_read_b32 v3, v45 offset:164
	ds_read_b32 v4, v45 offset:296
	ds_read_b32 v5, v45 offset:428
	ds_read_b32 v9, v45 offset:560
	ds_read_b32 v10, v45 offset:692
	ds_read_b32 v11, v45 offset:824
	ds_read_b32 v12, v45 offset:956
	s_waitcnt lgkmcnt(0)
	v_cvt_pk_bf16_f32 v2, v2, v3
	v_cvt_pk_bf16_f32 v3, v4, v5
	v_cvt_pk_bf16_f32 v4, v9, v10
	v_add_u32_e32 v10, 8, v8
	v_cvt_pk_bf16_f32 v5, v11, v12
	v_ashrrev_i32_e32 v11, 31, v10
	v_lshlrev_b64 v[10:11], 11, v[10:11]
	v_lshl_add_u64 v[10:11], v[6:7], 0, v[10:11]
	global_store_dwordx4 v[10:11], v[2:5], off nt
	ds_read_b32 v2, v45 offset:64
	ds_read_b32 v3, v45 offset:196
	ds_read_b32 v4, v45 offset:328
	ds_read_b32 v5, v45 offset:460
	ds_read_b32 v9, v45 offset:592
	ds_read_b32 v10, v45 offset:724
	ds_read_b32 v11, v45 offset:856
	ds_read_b32 v12, v45 offset:988
	s_waitcnt lgkmcnt(0)
	v_cvt_pk_bf16_f32 v2, v2, v3
	v_cvt_pk_bf16_f32 v3, v4, v5
	v_cvt_pk_bf16_f32 v4, v9, v10
	v_add_u32_e32 v10, 16, v8
	v_cvt_pk_bf16_f32 v5, v11, v12
	v_ashrrev_i32_e32 v11, 31, v10
	v_lshlrev_b64 v[10:11], 11, v[10:11]
	v_lshl_add_u64 v[10:11], v[6:7], 0, v[10:11]
	global_store_dwordx4 v[10:11], v[2:5], off nt
	ds_read_b32 v2, v45 offset:96
	ds_read_b32 v3, v45 offset:228
	ds_read_b32 v4, v45 offset:360
	ds_read_b32 v5, v45 offset:492
	ds_read_b32 v9, v45 offset:624
	ds_read_b32 v10, v45 offset:756
	ds_read_b32 v11, v45 offset:888
	ds_read_b32 v12, v45 offset:1020
	v_add_u32_e32 v8, 24, v8
	s_waitcnt lgkmcnt(0)
	v_cvt_pk_bf16_f32 v2, v2, v3
	v_cvt_pk_bf16_f32 v3, v4, v5
	v_cvt_pk_bf16_f32 v4, v9, v10
	v_ashrrev_i32_e32 v9, 31, v8
	v_lshlrev_b64 v[8:9], 11, v[8:9]
	v_cvt_pk_bf16_f32 v5, v11, v12
	v_lshl_add_u64 v[6:7], v[6:7], 0, v[8:9]
	global_store_dwordx4 v[6:7], v[2:5], off nt
	s_waitcnt lgkmcnt(0)
	s_add_i32 s47, s47, s33
	s_add_i32 s3, s3, s4
	s_cmpk_lt_i32 s47, 0x680
	s_cbranch_scc0 .LBB0_25

.LBB0_27:
	s_or_b64 exec, exec, s[44:45]
	s_waitcnt vmcnt(0)
	ds_write2_b32 v48, v2, v3 offset1:1
	ds_write2_b32 v48, v4, v5 offset0:2 offset1:3
	v_add_u32_e32 v2, 0x420, v48
	ds_write2_b32 v2, v10, v11 offset1:1
	v_add_u32_e32 v2, 0x428, v48
	ds_write2_b32 v2, v12, v13 offset1:1
	v_add_u32_e32 v2, 0x840, v48
	ds_write2_b32 v2, v6, v7 offset1:1
	v_add_u32_e32 v2, 0x848, v48
	ds_write2_b32 v2, v8, v9 offset1:1
	v_add_u32_e32 v2, 0xc60, v48
	ds_write2_b32 v2, v18, v19 offset1:1
	v_add_u32_e32 v2, 0xc68, v48
	ds_write2_b32 v2, v20, v21 offset1:1
	v_add_u32_e32 v2, 0x1080, v48
	ds_write2_b32 v2, v14, v15 offset1:1
	v_add_u32_e32 v2, 0x1088, v48
	ds_write2_b32 v2, v16, v17 offset1:1
	v_add_u32_e32 v2, 0x14a0, v48
	ds_write2_b32 v2, v26, v27 offset1:1
	v_add_u32_e32 v2, 0x14a8, v48
	ds_write2_b32 v2, v28, v29 offset1:1
	v_add_u32_e32 v2, 0x18c0, v48
	ds_write2_b32 v2, v22, v23 offset1:1
	v_add_u32_e32 v2, 0x18c8, v48
	ds_write2_b32 v2, v24, v25 offset1:1
	v_add_u32_e32 v2, 0x1ce0, v48
	ds_write2_b32 v2, v30, v31 offset1:1
	v_add_u32_e32 v2, 0x1ce8, v48
	ds_write2_b32 v2, v32, v33 offset1:1
	s_waitcnt lgkmcnt(0)
	ds_read_b32 v2, v47
	ds_read_b32 v3, v47 offset:132
	ds_read_b32 v4, v47 offset:264
	ds_read_b32 v5, v47 offset:396
	ds_read_b32 v8, v47 offset:528
	ds_read_b32 v9, v47 offset:660
	ds_read_b32 v10, v47 offset:792
	ds_read_b32 v11, v47 offset:924
	s_sub_i32 s0, 0, s1
	s_add_i32 s0, s0, s3
	s_waitcnt lgkmcnt(0)
	v_cvt_pk_bf16_f32 v2, v2, v3
	v_cvt_pk_bf16_f32 v3, v4, v5
	v_cvt_pk_bf16_f32 v4, v8, v9
	v_add_u32_e32 v8, s0, v46
	s_ashr_i32 s29, s28, 31
	v_ashrrev_i32_e32 v9, 31, v8
	v_lshl_add_u64 v[6:7], s[28:29], 1, v[38:39]
	v_cvt_pk_bf16_f32 v5, v10, v11
	v_lshlrev_b64 v[10:11], 11, v[8:9]
	v_lshl_add_u64 v[10:11], v[6:7], 0, v[10:11]
	global_store_dwordx4 v[10:11], v[2:5], off nt
	ds_read_b32 v2, v47 offset:32
	ds_read_b32 v3, v47 offset:164
	ds_read_b32 v4, v47 offset:296
	ds_read_b32 v5, v47 offset:428
	ds_read_b32 v9, v47 offset:560
	ds_read_b32 v10, v47 offset:692
	ds_read_b32 v11, v47 offset:824
	ds_read_b32 v12, v47 offset:956
	s_waitcnt lgkmcnt(0)
	v_cvt_pk_bf16_f32 v2, v2, v3
	v_cvt_pk_bf16_f32 v3, v4, v5
	v_cvt_pk_bf16_f32 v4, v9, v10
	v_add_u32_e32 v10, 8, v8
	v_cvt_pk_bf16_f32 v5, v11, v12
	v_ashrrev_i32_e32 v11, 31, v10
	v_lshlrev_b64 v[10:11], 11, v[10:11]
	v_lshl_add_u64 v[10:11], v[6:7], 0, v[10:11]
	global_store_dwordx4 v[10:11], v[2:5], off nt
	ds_read_b32 v2, v47 offset:64
	ds_read_b32 v3, v47 offset:196
	ds_read_b32 v4, v47 offset:328
	ds_read_b32 v5, v47 offset:460
	ds_read_b32 v9, v47 offset:592
	ds_read_b32 v10, v47 offset:724
	ds_read_b32 v11, v47 offset:856
	ds_read_b32 v12, v47 offset:988
	s_waitcnt lgkmcnt(0)
	v_cvt_pk_bf16_f32 v2, v2, v3
	v_cvt_pk_bf16_f32 v3, v4, v5
	v_cvt_pk_bf16_f32 v4, v9, v10
	v_add_u32_e32 v10, 16, v8
	v_cvt_pk_bf16_f32 v5, v11, v12
	v_ashrrev_i32_e32 v11, 31, v10
	v_lshlrev_b64 v[10:11], 11, v[10:11]
	v_lshl_add_u64 v[10:11], v[6:7], 0, v[10:11]
	global_store_dwordx4 v[10:11], v[2:5], off nt
	ds_read_b32 v2, v47 offset:96
	ds_read_b32 v3, v47 offset:228
	ds_read_b32 v4, v47 offset:360
	ds_read_b32 v5, v47 offset:492
	ds_read_b32 v9, v47 offset:624
	ds_read_b32 v10, v47 offset:756
	ds_read_b32 v11, v47 offset:888
	ds_read_b32 v12, v47 offset:1020
	v_add_u32_e32 v8, 24, v8
	s_waitcnt lgkmcnt(0)
	v_cvt_pk_bf16_f32 v2, v2, v3
	v_cvt_pk_bf16_f32 v3, v4, v5
	v_cvt_pk_bf16_f32 v4, v9, v10
	v_ashrrev_i32_e32 v9, 31, v8
	v_lshlrev_b64 v[8:9], 11, v[8:9]
	v_cvt_pk_bf16_f32 v5, v11, v12
	v_lshl_add_u64 v[6:7], v[6:7], 0, v[8:9]
	global_store_dwordx4 v[6:7], v[2:5], off nt
	s_waitcnt lgkmcnt(0)
	s_add_i32 s46, s46, s33
	s_add_i32 s3, s3, s4
	s_cmpk_lt_i32 s46, 0x200
	s_cbranch_scc0 .LBB0_44

.LBB0_46:
	s_or_b64 exec, exec, s[30:31]
	s_waitcnt vmcnt(0)
	ds_write2_b32 v46, v2, v3 offset1:1
	ds_write2_b32 v46, v4, v5 offset0:2 offset1:3
	v_add_u32_e32 v2, 0x420, v46
	ds_write2_b32 v2, v10, v11 offset1:1
	v_add_u32_e32 v2, 0x428, v46
	ds_write2_b32 v2, v12, v13 offset1:1
	v_add_u32_e32 v2, 0x840, v46
	ds_write2_b32 v2, v6, v7 offset1:1
	v_add_u32_e32 v2, 0x848, v46
	ds_write2_b32 v2, v8, v9 offset1:1
	v_add_u32_e32 v2, 0xc60, v46
	ds_write2_b32 v2, v18, v19 offset1:1
	v_add_u32_e32 v2, 0xc68, v46
	ds_write2_b32 v2, v20, v21 offset1:1
	v_add_u32_e32 v2, 0x1080, v46
	ds_write2_b32 v2, v14, v15 offset1:1
	v_add_u32_e32 v2, 0x1088, v46
	ds_write2_b32 v2, v16, v17 offset1:1
	v_add_u32_e32 v2, 0x14a0, v46
	ds_write2_b32 v2, v26, v27 offset1:1
	v_add_u32_e32 v2, 0x14a8, v46
	ds_write2_b32 v2, v28, v29 offset1:1
	v_add_u32_e32 v2, 0x18c0, v46
	ds_write2_b32 v2, v22, v23 offset1:1
	v_add_u32_e32 v2, 0x18c8, v46
	ds_write2_b32 v2, v24, v25 offset1:1
	v_add_u32_e32 v2, 0x1ce0, v46
	ds_write2_b32 v2, v30, v31 offset1:1
	v_add_u32_e32 v2, 0x1ce8, v46
	ds_write2_b32 v2, v32, v33 offset1:1
	s_waitcnt lgkmcnt(0)
	ds_read_b32 v2, v45
	ds_read_b32 v3, v45 offset:132
	ds_read_b32 v4, v45 offset:264
	ds_read_b32 v5, v45 offset:396
	ds_read_b32 v8, v45 offset:528
	ds_read_b32 v9, v45 offset:660
	ds_read_b32 v10, v45 offset:792
	ds_read_b32 v11, v45 offset:924
	s_waitcnt lgkmcnt(0)
	v_cvt_pk_bf16_f32 v2, v2, v3
	v_cvt_pk_bf16_f32 v3, v4, v5
	v_cvt_pk_bf16_f32 v4, v8, v9
	v_add_u32_e32 v8, s6, v43
	s_ashr_i32 s29, s28, 31
	v_ashrrev_i32_e32 v9, 31, v8
	v_lshl_add_u64 v[6:7], s[28:29], 1, v[38:39]
	v_cvt_pk_bf16_f32 v5, v10, v11
	v_lshlrev_b64 v[10:11], 11, v[8:9]
	v_lshl_add_u64 v[10:11], v[6:7], 0, v[10:11]
	global_store_dwordx4 v[10:11], v[2:5], off nt
	ds_read_b32 v2, v45 offset:32
	ds_read_b32 v3, v45 offset:164
	ds_read_b32 v4, v45 offset:296
	ds_read_b32 v5, v45 offset:428
	ds_read_b32 v9, v45 offset:560
	ds_read_b32 v10, v45 offset:692
	ds_read_b32 v11, v45 offset:824
	ds_read_b32 v12, v45 offset:956
	s_waitcnt lgkmcnt(0)
	v_cvt_pk_bf16_f32 v2, v2, v3
	v_cvt_pk_bf16_f32 v3, v4, v5
	v_cvt_pk_bf16_f32 v4, v9, v10
	v_add_u32_e32 v10, 8, v8
	v_cvt_pk_bf16_f32 v5, v11, v12
	v_ashrrev_i32_e32 v11, 31, v10
	v_lshlrev_b64 v[10:11], 11, v[10:11]
	v_lshl_add_u64 v[10:11], v[6:7], 0, v[10:11]
	global_store_dwordx4 v[10:11], v[2:5], off nt
	ds_read_b32 v2, v45 offset:64
	ds_read_b32 v3, v45 offset:196
	ds_read_b32 v4, v45 offset:328
	ds_read_b32 v5, v45 offset:460
	ds_read_b32 v9, v45 offset:592
	ds_read_b32 v10, v45 offset:724
	ds_read_b32 v11, v45 offset:856
	ds_read_b32 v12, v45 offset:988
	s_waitcnt lgkmcnt(0)
	v_cvt_pk_bf16_f32 v2, v2, v3
	v_cvt_pk_bf16_f32 v3, v4, v5
	v_cvt_pk_bf16_f32 v4, v9, v10
	v_add_u32_e32 v10, 16, v8
	v_cvt_pk_bf16_f32 v5, v11, v12
	v_ashrrev_i32_e32 v11, 31, v10
	v_lshlrev_b64 v[10:11], 11, v[10:11]
	v_lshl_add_u64 v[10:11], v[6:7], 0, v[10:11]
	global_store_dwordx4 v[10:11], v[2:5], off nt
	ds_read_b32 v2, v45 offset:96
	ds_read_b32 v3, v45 offset:228
	ds_read_b32 v4, v45 offset:360
	ds_read_b32 v5, v45 offset:492
	ds_read_b32 v9, v45 offset:624
	ds_read_b32 v10, v45 offset:756
	ds_read_b32 v11, v45 offset:888
	ds_read_b32 v12, v45 offset:1020
	v_add_u32_e32 v8, 24, v8
	s_waitcnt lgkmcnt(0)
	v_cvt_pk_bf16_f32 v2, v2, v3
	v_cvt_pk_bf16_f32 v3, v4, v5
	v_cvt_pk_bf16_f32 v4, v9, v10
	v_ashrrev_i32_e32 v9, 31, v8
	v_lshlrev_b64 v[8:9], 11, v[8:9]
	v_cvt_pk_bf16_f32 v5, v11, v12
	v_lshl_add_u64 v[6:7], v[6:7], 0, v[8:9]
	global_store_dwordx4 v[6:7], v[2:5], off nt
	s_waitcnt lgkmcnt(0)
	s_add_i32 s45, s45, s33
	s_add_i32 s3, s3, s4
	s_cmpk_lt_i32 s45, 0x680
	s_cbranch_scc0 .LBB0_63

.LBB0_65:
	s_or_b64 exec, exec, s[28:29]
	s_waitcnt vmcnt(0)
	ds_write2_b32 v48, v2, v3 offset1:1
	ds_write2_b32 v48, v4, v5 offset0:2 offset1:3
	v_add_u32_e32 v2, 0x420, v48
	ds_write2_b32 v2, v10, v11 offset1:1
	v_add_u32_e32 v2, 0x428, v48
	ds_write2_b32 v2, v12, v13 offset1:1
	v_add_u32_e32 v2, 0x840, v48
	ds_write2_b32 v2, v6, v7 offset1:1
	v_add_u32_e32 v2, 0x848, v48
	ds_write2_b32 v2, v8, v9 offset1:1
	v_add_u32_e32 v2, 0xc60, v48
	ds_write2_b32 v2, v18, v19 offset1:1
	v_add_u32_e32 v2, 0xc68, v48
	ds_write2_b32 v2, v20, v21 offset1:1
	v_add_u32_e32 v2, 0x1080, v48
	ds_write2_b32 v2, v14, v15 offset1:1
	v_add_u32_e32 v2, 0x1088, v48
	ds_write2_b32 v2, v16, v17 offset1:1
	v_add_u32_e32 v2, 0x14a0, v48
	ds_write2_b32 v2, v26, v27 offset1:1
	v_add_u32_e32 v2, 0x14a8, v48
	ds_write2_b32 v2, v28, v29 offset1:1
	v_add_u32_e32 v2, 0x18c0, v48
	ds_write2_b32 v2, v22, v23 offset1:1
	v_add_u32_e32 v2, 0x18c8, v48
	ds_write2_b32 v2, v24, v25 offset1:1
	v_add_u32_e32 v2, 0x1ce0, v48
	ds_write2_b32 v2, v30, v31 offset1:1
	v_add_u32_e32 v2, 0x1ce8, v48
	ds_write2_b32 v2, v32, v33 offset1:1
	s_waitcnt lgkmcnt(0)
	ds_read_b32 v2, v47
	ds_read_b32 v3, v47 offset:132
	ds_read_b32 v4, v47 offset:264
	ds_read_b32 v5, v47 offset:396
	ds_read_b32 v8, v47 offset:528
	ds_read_b32 v9, v47 offset:660
	ds_read_b32 v10, v47 offset:792
	ds_read_b32 v11, v47 offset:924
	s_sub_i32 s0, 0, s1
	s_add_i32 s0, s0, s3
	s_waitcnt lgkmcnt(0)
	v_cvt_pk_bf16_f32 v2, v2, v3
	v_cvt_pk_bf16_f32 v3, v4, v5
	v_cvt_pk_bf16_f32 v4, v8, v9
	v_add_u32_e32 v8, s0, v46
	s_ashr_i32 s25, s24, 31
	v_ashrrev_i32_e32 v9, 31, v8
	v_lshl_add_u64 v[6:7], s[24:25], 1, v[38:39]
	v_cvt_pk_bf16_f32 v5, v10, v11
	v_lshlrev_b64 v[10:11], 11, v[8:9]
	v_lshl_add_u64 v[10:11], v[6:7], 0, v[10:11]
	global_store_dwordx4 v[10:11], v[2:5], off nt
	ds_read_b32 v2, v47 offset:32
	ds_read_b32 v3, v47 offset:164
	ds_read_b32 v4, v47 offset:296
	ds_read_b32 v5, v47 offset:428
	ds_read_b32 v9, v47 offset:560
	ds_read_b32 v10, v47 offset:692
	ds_read_b32 v11, v47 offset:824
	ds_read_b32 v12, v47 offset:956
	s_waitcnt lgkmcnt(0)
	v_cvt_pk_bf16_f32 v2, v2, v3
	v_cvt_pk_bf16_f32 v3, v4, v5
	v_cvt_pk_bf16_f32 v4, v9, v10
	v_add_u32_e32 v10, 8, v8
	v_cvt_pk_bf16_f32 v5, v11, v12
	v_ashrrev_i32_e32 v11, 31, v10
	v_lshlrev_b64 v[10:11], 11, v[10:11]
	v_lshl_add_u64 v[10:11], v[6:7], 0, v[10:11]
	global_store_dwordx4 v[10:11], v[2:5], off nt
	ds_read_b32 v2, v47 offset:64
	ds_read_b32 v3, v47 offset:196
	ds_read_b32 v4, v47 offset:328
	ds_read_b32 v5, v47 offset:460
	ds_read_b32 v9, v47 offset:592
	ds_read_b32 v10, v47 offset:724
	ds_read_b32 v11, v47 offset:856
	ds_read_b32 v12, v47 offset:988
	s_waitcnt lgkmcnt(0)
	v_cvt_pk_bf16_f32 v2, v2, v3
	v_cvt_pk_bf16_f32 v3, v4, v5
	v_cvt_pk_bf16_f32 v4, v9, v10
	v_add_u32_e32 v10, 16, v8
	v_cvt_pk_bf16_f32 v5, v11, v12
	v_ashrrev_i32_e32 v11, 31, v10
	v_lshlrev_b64 v[10:11], 11, v[10:11]
	v_lshl_add_u64 v[10:11], v[6:7], 0, v[10:11]
	global_store_dwordx4 v[10:11], v[2:5], off nt
	ds_read_b32 v2, v47 offset:96
	ds_read_b32 v3, v47 offset:228
	ds_read_b32 v4, v47 offset:360
	ds_read_b32 v5, v47 offset:492
	ds_read_b32 v9, v47 offset:624
	ds_read_b32 v10, v47 offset:756
	ds_read_b32 v11, v47 offset:888
	ds_read_b32 v12, v47 offset:1020
	v_add_u32_e32 v8, 24, v8
	s_waitcnt lgkmcnt(0)
	v_cvt_pk_bf16_f32 v2, v2, v3
	v_cvt_pk_bf16_f32 v3, v4, v5
	v_cvt_pk_bf16_f32 v4, v9, v10
	v_ashrrev_i32_e32 v9, 31, v8
	v_lshlrev_b64 v[8:9], 11, v[8:9]
	v_cvt_pk_bf16_f32 v5, v11, v12
	v_lshl_add_u64 v[6:7], v[6:7], 0, v[8:9]
	global_store_dwordx4 v[6:7], v[2:5], off nt
	s_waitcnt lgkmcnt(0)
	s_add_i32 s30, s30, s33
	s_add_i32 s3, s3, s4
	s_cmpk_lt_i32 s30, 0x200
	s_cbranch_scc0 .LBB0_82

.LBB0_84:
	s_or_b64 exec, exec, s[26:27]
	s_waitcnt vmcnt(0)
	ds_write2_b32 v48, v2, v3 offset1:1
	ds_write2_b32 v48, v4, v5 offset0:2 offset1:3
	v_add_u32_e32 v2, 0x420, v48
	ds_write2_b32 v2, v10, v11 offset1:1
	v_add_u32_e32 v2, 0x428, v48
	ds_write2_b32 v2, v12, v13 offset1:1
	v_add_u32_e32 v2, 0x840, v48
	ds_write2_b32 v2, v6, v7 offset1:1
	v_add_u32_e32 v2, 0x848, v48
	ds_write2_b32 v2, v8, v9 offset1:1
	v_add_u32_e32 v2, 0xc60, v48
	ds_write2_b32 v2, v18, v19 offset1:1
	v_add_u32_e32 v2, 0xc68, v48
	ds_write2_b32 v2, v20, v21 offset1:1
	v_add_u32_e32 v2, 0x1080, v48
	ds_write2_b32 v2, v14, v15 offset1:1
	v_add_u32_e32 v2, 0x1088, v48
	ds_write2_b32 v2, v16, v17 offset1:1
	v_add_u32_e32 v2, 0x14a0, v48
	ds_write2_b32 v2, v26, v27 offset1:1
	v_add_u32_e32 v2, 0x14a8, v48
	ds_write2_b32 v2, v28, v29 offset1:1
	v_add_u32_e32 v2, 0x18c0, v48
	ds_write2_b32 v2, v22, v23 offset1:1
	v_add_u32_e32 v2, 0x18c8, v48
	ds_write2_b32 v2, v24, v25 offset1:1
	v_add_u32_e32 v2, 0x1ce0, v48
	ds_write2_b32 v2, v30, v31 offset1:1
	v_add_u32_e32 v2, 0x1ce8, v48
	ds_write2_b32 v2, v32, v33 offset1:1
	s_waitcnt lgkmcnt(0)
	ds_read_b32 v2, v47
	ds_read_b32 v3, v47 offset:132
	ds_read_b32 v4, v47 offset:264
	ds_read_b32 v5, v47 offset:396
	ds_read_b32 v8, v47 offset:528
	ds_read_b32 v9, v47 offset:660
	ds_read_b32 v10, v47 offset:792
	ds_read_b32 v11, v47 offset:924
	s_sub_i32 s0, 0, s1
	s_add_i32 s0, s0, s3
	s_waitcnt lgkmcnt(0)
	v_cvt_pk_bf16_f32 v2, v2, v3
	v_cvt_pk_bf16_f32 v3, v4, v5
	v_cvt_pk_bf16_f32 v4, v8, v9
	v_add_u32_e32 v8, s0, v46
	s_ashr_i32 s25, s24, 31
	v_ashrrev_i32_e32 v9, 31, v8
	v_lshl_add_u64 v[6:7], s[24:25], 1, v[38:39]
	v_cvt_pk_bf16_f32 v5, v10, v11
	v_lshlrev_b64 v[10:11], 11, v[8:9]
	v_lshl_add_u64 v[10:11], v[6:7], 0, v[10:11]
	global_store_dwordx4 v[10:11], v[2:5], off nt
	ds_read_b32 v2, v47 offset:32
	ds_read_b32 v3, v47 offset:164
	ds_read_b32 v4, v47 offset:296
	ds_read_b32 v5, v47 offset:428
	ds_read_b32 v9, v47 offset:560
	ds_read_b32 v10, v47 offset:692
	ds_read_b32 v11, v47 offset:824
	ds_read_b32 v12, v47 offset:956
	s_waitcnt lgkmcnt(0)
	v_cvt_pk_bf16_f32 v2, v2, v3
	v_cvt_pk_bf16_f32 v3, v4, v5
	v_cvt_pk_bf16_f32 v4, v9, v10
	v_add_u32_e32 v10, 8, v8
	v_cvt_pk_bf16_f32 v5, v11, v12
	v_ashrrev_i32_e32 v11, 31, v10
	v_lshlrev_b64 v[10:11], 11, v[10:11]
	v_lshl_add_u64 v[10:11], v[6:7], 0, v[10:11]
	global_store_dwordx4 v[10:11], v[2:5], off nt
	ds_read_b32 v2, v47 offset:64
	ds_read_b32 v3, v47 offset:196
	ds_read_b32 v4, v47 offset:328
	ds_read_b32 v5, v47 offset:460
	ds_read_b32 v9, v47 offset:592
	ds_read_b32 v10, v47 offset:724
	ds_read_b32 v11, v47 offset:856
	ds_read_b32 v12, v47 offset:988
	s_waitcnt lgkmcnt(0)
	v_cvt_pk_bf16_f32 v2, v2, v3
	v_cvt_pk_bf16_f32 v3, v4, v5
	v_cvt_pk_bf16_f32 v4, v9, v10
	v_add_u32_e32 v10, 16, v8
	v_cvt_pk_bf16_f32 v5, v11, v12
	v_ashrrev_i32_e32 v11, 31, v10
	v_lshlrev_b64 v[10:11], 11, v[10:11]
	v_lshl_add_u64 v[10:11], v[6:7], 0, v[10:11]
	global_store_dwordx4 v[10:11], v[2:5], off nt
	ds_read_b32 v2, v47 offset:96
	ds_read_b32 v3, v47 offset:228
	ds_read_b32 v4, v47 offset:360
	ds_read_b32 v5, v47 offset:492
	ds_read_b32 v9, v47 offset:624
	ds_read_b32 v10, v47 offset:756
	ds_read_b32 v11, v47 offset:888
	ds_read_b32 v12, v47 offset:1020
	v_add_u32_e32 v8, 24, v8
	s_waitcnt lgkmcnt(0)
	v_cvt_pk_bf16_f32 v2, v2, v3
	v_cvt_pk_bf16_f32 v3, v4, v5
	v_cvt_pk_bf16_f32 v4, v9, v10
	v_ashrrev_i32_e32 v9, 31, v8
	v_lshlrev_b64 v[8:9], 11, v[8:9]
	v_cvt_pk_bf16_f32 v5, v11, v12
	v_lshl_add_u64 v[6:7], v[6:7], 0, v[8:9]
	global_store_dwordx4 v[6:7], v[2:5], off nt
	s_waitcnt lgkmcnt(0)
	s_add_i32 s28, s28, s33
	s_add_i32 s3, s3, s4
	s_cmpk_lt_i32 s28, 0x400
	s_cbranch_scc0 .LBB0_101

.LBB0_105:
	s_or_b64 exec, exec, s[24:25]
	s_waitcnt vmcnt(0)
	ds_write2_b32 v54, v2, v3 offset1:1
	ds_write2_b32 v54, v4, v5 offset0:2 offset1:3
	v_add_u32_e32 v2, 0x420, v54
	ds_write2_b32 v2, v10, v11 offset1:1
	v_add_u32_e32 v2, 0x428, v54
	ds_write2_b32 v2, v12, v13 offset1:1
	v_add_u32_e32 v2, 0x840, v54
	ds_write2_b32 v2, v6, v7 offset1:1
	v_add_u32_e32 v2, 0x848, v54
	ds_write2_b32 v2, v8, v9 offset1:1
	v_add_u32_e32 v2, 0xc60, v54
	ds_write2_b32 v2, v18, v19 offset1:1
	v_add_u32_e32 v2, 0xc68, v54
	ds_write2_b32 v2, v20, v21 offset1:1
	v_add_u32_e32 v2, 0x1080, v54
	ds_write2_b32 v2, v14, v15 offset1:1
	v_add_u32_e32 v2, 0x1088, v54
	ds_write2_b32 v2, v16, v17 offset1:1
	v_add_u32_e32 v2, 0x14a0, v54
	ds_write2_b32 v2, v26, v27 offset1:1
	v_add_u32_e32 v2, 0x14a8, v54
	ds_write2_b32 v2, v28, v29 offset1:1
	v_add_u32_e32 v2, 0x18c0, v54
	ds_write2_b32 v2, v22, v23 offset1:1
	v_add_u32_e32 v2, 0x18c8, v54
	ds_write2_b32 v2, v24, v25 offset1:1
	v_add_u32_e32 v2, 0x1ce0, v54
	ds_write2_b32 v2, v30, v31 offset1:1
	v_add_u32_e32 v2, 0x1ce8, v54
	ds_write2_b32 v2, v32, v33 offset1:1
	s_waitcnt lgkmcnt(0)
	ds_read_b32 v2, v52
	ds_read_b32 v3, v52 offset:132
	ds_read_b32 v4, v52 offset:264
	ds_read_b32 v5, v52 offset:396
	ds_read_b32 v8, v52 offset:528
	ds_read_b32 v9, v52 offset:660
	ds_read_b32 v10, v52 offset:792
	ds_read_b32 v11, v52 offset:924
	s_sub_i32 s0, 0, s1
	s_add_i32 s0, s0, s3
	s_waitcnt lgkmcnt(0)
	v_cvt_pk_bf16_f32 v2, v2, v3
	v_cvt_pk_bf16_f32 v3, v4, v5
	v_cvt_pk_bf16_f32 v4, v8, v9
	v_add_u32_e32 v8, s0, v35
	s_ashr_i32 s9, s8, 31
	v_ashrrev_i32_e32 v9, 31, v8
	v_lshl_add_u64 v[6:7], s[8:9], 1, v[42:43]
	v_cvt_pk_bf16_f32 v5, v10, v11
	v_lshlrev_b64 v[10:11], 11, v[8:9]
	v_lshl_add_u64 v[10:11], v[6:7], 0, v[10:11]
	global_store_dwordx4 v[10:11], v[2:5], off nt
	ds_read_b32 v2, v52 offset:32
	ds_read_b32 v3, v52 offset:164
	ds_read_b32 v4, v52 offset:296
	ds_read_b32 v5, v52 offset:428
	ds_read_b32 v9, v52 offset:560
	ds_read_b32 v10, v52 offset:692
	ds_read_b32 v11, v52 offset:824
	ds_read_b32 v12, v52 offset:956
	s_waitcnt lgkmcnt(0)
	v_cvt_pk_bf16_f32 v2, v2, v3
	v_cvt_pk_bf16_f32 v3, v4, v5
	v_cvt_pk_bf16_f32 v4, v9, v10
	v_add_u32_e32 v10, 8, v8
	v_cvt_pk_bf16_f32 v5, v11, v12
	v_ashrrev_i32_e32 v11, 31, v10
	v_lshlrev_b64 v[10:11], 11, v[10:11]
	v_lshl_add_u64 v[10:11], v[6:7], 0, v[10:11]
	global_store_dwordx4 v[10:11], v[2:5], off nt
	ds_read_b32 v2, v52 offset:64
	ds_read_b32 v3, v52 offset:196
	ds_read_b32 v4, v52 offset:328
	ds_read_b32 v5, v52 offset:460
	ds_read_b32 v9, v52 offset:592
	ds_read_b32 v10, v52 offset:724
	ds_read_b32 v11, v52 offset:856
	ds_read_b32 v12, v52 offset:988
	s_waitcnt lgkmcnt(0)
	v_cvt_pk_bf16_f32 v2, v2, v3
	v_cvt_pk_bf16_f32 v3, v4, v5
	v_cvt_pk_bf16_f32 v4, v9, v10
	v_add_u32_e32 v10, 16, v8
	v_cvt_pk_bf16_f32 v5, v11, v12
	v_ashrrev_i32_e32 v11, 31, v10
	v_lshlrev_b64 v[10:11], 11, v[10:11]
	v_lshl_add_u64 v[10:11], v[6:7], 0, v[10:11]
	global_store_dwordx4 v[10:11], v[2:5], off nt
	ds_read_b32 v2, v52 offset:96
	ds_read_b32 v3, v52 offset:228
	ds_read_b32 v4, v52 offset:360
	ds_read_b32 v5, v52 offset:492
	ds_read_b32 v9, v52 offset:624
	ds_read_b32 v10, v52 offset:756
	ds_read_b32 v11, v52 offset:888
	ds_read_b32 v12, v52 offset:1020
	v_add_u32_e32 v8, 24, v8
	s_waitcnt lgkmcnt(0)
	v_cvt_pk_bf16_f32 v2, v2, v3
	v_cvt_pk_bf16_f32 v3, v4, v5
	v_cvt_pk_bf16_f32 v4, v9, v10
	v_ashrrev_i32_e32 v9, 31, v8
	v_lshlrev_b64 v[8:9], 11, v[8:9]
	v_cvt_pk_bf16_f32 v5, v11, v12
	v_lshl_add_u64 v[6:7], v[6:7], 0, v[8:9]
	global_store_dwordx4 v[6:7], v[2:5], off nt
	s_waitcnt lgkmcnt(0)
	s_add_i32 s26, s26, s33
	s_add_i32 s3, s3, s4
	s_cmpk_lt_i32 s26, 0x200
	s_cbranch_scc0 .LBB0_122

.LBB0_127:
	s_ashr_i32 s0, s1, 31
	s_lshr_b32 s0, s0, 29
	s_add_i32 s0, s1, s0
	s_ashr_i32 s0, s0, 3
	s_lshl_b32 s26, s0, 6
	s_lshl_b32 s24, s0, 8
	v_or_b32_e32 v14, s26, v52
	s_sub_i32 s24, s41, s24
	v_or_b32_e32 v16, 8, v14
	v_or_b32_e32 v18, 16, v14
	v_or_b32_e32 v20, 24, v14
	v_or_b32_e32 v22, 32, v14
	v_or_b32_e32 v24, 40, v14
	v_or_b32_e32 v26, 48, v14
	v_or_b32_e32 v28, 56, v14
	s_ashr_i32 s25, s24, 31
	v_ashrrev_i32_e32 v15, 31, v14
	v_ashrrev_i32_e32 v17, 31, v16
	v_ashrrev_i32_e32 v19, 31, v18
	v_ashrrev_i32_e32 v21, 31, v20
	v_ashrrev_i32_e32 v23, 31, v22
	v_ashrrev_i32_e32 v25, 31, v24
	v_ashrrev_i32_e32 v27, 31, v26
	v_ashrrev_i32_e32 v29, 31, v28
	v_lshl_add_u64 v[30:31], s[24:25], 2, v[4:5]
	v_lshlrev_b64 v[14:15], 10, v[14:15]
	v_lshlrev_b64 v[32:33], 10, v[16:17]
	v_lshlrev_b64 v[18:19], 10, v[18:19]
	v_lshlrev_b64 v[20:21], 10, v[20:21]
	v_lshlrev_b64 v[22:23], 10, v[22:23]
	v_lshlrev_b64 v[24:25], 10, v[24:25]
	v_lshlrev_b64 v[26:27], 10, v[26:27]
	v_lshlrev_b64 v[28:29], 10, v[28:29]
	v_lshl_add_u64 v[14:15], v[30:31], 0, v[14:15]
	v_lshl_add_u64 v[32:33], v[30:31], 0, v[32:33]
	v_lshl_add_u64 v[42:43], v[30:31], 0, v[18:19]
	v_lshl_add_u64 v[44:45], v[30:31], 0, v[20:21]
	v_lshl_add_u64 v[46:47], v[30:31], 0, v[22:23]
	v_lshl_add_u64 v[48:49], v[30:31], 0, v[24:25]
	v_lshl_add_u64 v[62:63], v[30:31], 0, v[26:27]
	v_lshl_add_u64 v[64:65], v[30:31], 0, v[28:29]
	global_load_dwordx4 v[14:17], v[14:15], off nt
	s_nop 0
	global_load_dwordx4 v[18:21], v[32:33], off nt
	global_load_dwordx4 v[22:25], v[42:43], off nt
	global_load_dwordx4 v[26:29], v[44:45], off nt
	s_nop 0
	global_load_dwordx4 v[30:33], v[46:47], off nt
	global_load_dwordx4 v[42:45], v[48:49], off nt
	s_nop 0
	global_load_dwordx4 v[46:49], v[62:63], off nt
	s_nop 0
	global_load_dwordx4 v[62:65], v[64:65], off nt
	s_lshl_b32 s0, s0, 9
	s_sub_i32 s0, s40, s0
	s_and_b32 s0, s0, 0xffffff00
	s_and_b32 s24, s24, 0x60
	s_add_i32 s0, s0, s31
	s_or_b32 s0, s24, s0
	v_or_b32_e32 v68, s0, v52
	s_ashr_i32 s27, s26, 31
	v_ashrrev_i32_e32 v69, 31, v68
	v_lshl_add_u64 v[66:67], s[26:27], 1, v[2:3]
	v_lshlrev_b64 v[68:69], 9, v[68:69]
	v_lshl_add_u64 v[68:69], v[66:67], 0, v[68:69]
	v_or_b32_e32 v70, s0, v1
	v_ashrrev_i32_e32 v71, 31, v70
	v_lshlrev_b64 v[70:71], 9, v[70:71]
	v_lshl_add_u64 v[70:71], v[66:67], 0, v[70:71]
	v_or_b32_e32 v72, s0, v50
	v_ashrrev_i32_e32 v73, 31, v72
	v_lshlrev_b64 v[72:73], 9, v[72:73]
	v_lshl_add_u64 v[72:73], v[66:67], 0, v[72:73]
	v_or_b32_e32 v74, s0, v51
	v_ashrrev_i32_e32 v75, 31, v74
	v_lshlrev_b64 v[74:75], 9, v[74:75]
	s_add_i32 s1, s1, s33
	s_add_i32 s41, s41, s3
	s_add_i32 s40, s40, s30
	s_cmp_lt_i32 s1, 32
	s_waitcnt vmcnt(0)
	ds_write2_b32 v57, v14, v15 offset1:1
	ds_write2_b32 v57, v16, v17 offset0:2 offset1:3
	ds_write2_b32 v58, v18, v19 offset1:1
	ds_write2_b32 v58, v20, v21 offset0:2 offset1:3
	ds_write2_b32 v59, v22, v23 offset1:1
	ds_write2_b32 v59, v24, v25 offset0:2 offset1:3
	ds_write2_b32 v60, v26, v27 offset1:1
	ds_write2_b32 v60, v28, v29 offset0:2 offset1:3
	ds_write2_b32 v6, v30, v31 offset1:1
	ds_write2_b32 v7, v32, v33 offset1:1
	ds_write2_b32 v8, v42, v43 offset1:1
	ds_write2_b32 v9, v44, v45 offset1:1
	ds_write2_b32 v10, v46, v47 offset1:1
	ds_write2_b32 v11, v48, v49 offset1:1
	ds_write2_b32 v12, v62, v63 offset1:1
	ds_write2_b32 v13, v64, v65 offset1:1
	s_waitcnt lgkmcnt(0)
	ds_read2_b32 v[14:15], v53 offset1:33
	ds_read2_b32 v[16:17], v53 offset0:66 offset1:99
	ds_read2_b32 v[18:19], v53 offset0:132 offset1:165
	ds_read2_b32 v[20:21], v53 offset0:198 offset1:231
	v_lshl_add_u64 v[22:23], v[66:67], 0, v[74:75]
	s_waitcnt lgkmcnt(0)
	v_cvt_pk_bf16_f32 v14, v14, v15
	s_waitcnt lgkmcnt(2)
	v_cvt_pk_bf16_f32 v15, v16, v17
	s_waitcnt lgkmcnt(1)
	v_cvt_pk_bf16_f32 v16, v18, v19
	s_waitcnt lgkmcnt(0)
	v_cvt_pk_bf16_f32 v17, v20, v21
	global_store_dwordx4 v[68:69], v[14:17], off nt
	ds_read2_b32 v[14:15], v54 offset1:33
	ds_read2_b32 v[16:17], v54 offset0:66 offset1:99
	ds_read2_b32 v[18:19], v54 offset0:132 offset1:165
	ds_read2_b32 v[20:21], v54 offset0:198 offset1:231
	s_waitcnt lgkmcnt(0)
	v_cvt_pk_bf16_f32 v14, v14, v15
	v_cvt_pk_bf16_f32 v15, v16, v17
	v_cvt_pk_bf16_f32 v16, v18, v19
	v_cvt_pk_bf16_f32 v17, v20, v21
	global_store_dwordx4 v[70:71], v[14:17], off nt
	ds_read2_b32 v[14:15], v55 offset1:33
	ds_read2_b32 v[16:17], v55 offset0:66 offset1:99
	ds_read2_b32 v[18:19], v55 offset0:132 offset1:165
	ds_read2_b32 v[20:21], v55 offset0:198 offset1:231
	s_waitcnt lgkmcnt(0)
	v_cvt_pk_bf16_f32 v14, v14, v15
	v_cvt_pk_bf16_f32 v15, v16, v17
	v_cvt_pk_bf16_f32 v16, v18, v19
	v_cvt_pk_bf16_f32 v17, v20, v21
	global_store_dwordx4 v[72:73], v[14:17], off nt
	ds_read2_b32 v[14:15], v56 offset1:33
	ds_read2_b32 v[16:17], v56 offset0:66 offset1:99
	ds_read2_b32 v[18:19], v56 offset0:132 offset1:165
	ds_read2_b32 v[20:21], v56 offset0:198 offset1:231
	s_waitcnt lgkmcnt(0)
	v_cvt_pk_bf16_f32 v14, v14, v15
	v_cvt_pk_bf16_f32 v15, v16, v17
	v_cvt_pk_bf16_f32 v16, v18, v19
	v_cvt_pk_bf16_f32 v17, v20, v21
	global_store_dwordx4 v[22:23], v[14:17], off nt
	s_waitcnt lgkmcnt(0)
	s_cbranch_scc1 .LBB0_127
	s_branch .LBB0_124

.LBB0_130:
	s_or_b64 exec, exec, s[24:25]
	s_waitcnt vmcnt(0)
	ds_write2_b32 v57, v6, v7 offset1:1
	ds_write2_b32 v57, v8, v9 offset0:2 offset1:3
	ds_write2_b32 v58, v2, v3 offset1:1
	ds_write2_b32 v58, v4, v5 offset0:2 offset1:3
	ds_write2_b32 v59, v14, v15 offset1:1
	ds_write2_b32 v59, v16, v17 offset0:2 offset1:3
	ds_write2_b32 v60, v10, v11 offset1:1
	ds_write2_b32 v60, v12, v13 offset0:2 offset1:3
	v_add_u32_e32 v2, 0x1080, v57
	ds_write2_b32 v2, v22, v23 offset1:1
	v_add_u32_e32 v2, 0x1088, v57
	ds_write2_b32 v2, v24, v25 offset1:1
	v_add_u32_e32 v2, 0x14a0, v57
	ds_write2_b32 v2, v18, v19 offset1:1
	v_add_u32_e32 v2, 0x14a8, v57
	ds_write2_b32 v2, v20, v21 offset1:1
	v_add_u32_e32 v2, 0x18c0, v57
	ds_write2_b32 v2, v30, v31 offset1:1
	v_add_u32_e32 v2, 0x18c8, v57
	ds_write2_b32 v2, v32, v33 offset1:1
	v_add_u32_e32 v2, 0x1ce0, v57
	ds_write2_b32 v2, v26, v27 offset1:1
	v_add_u32_e32 v2, 0x1ce8, v57
	ds_write2_b32 v2, v28, v29 offset1:1
	s_waitcnt lgkmcnt(0)
	ds_read2_b32 v[2:3], v53 offset1:33
	ds_read2_b32 v[4:5], v53 offset0:66 offset1:99
	ds_read2_b32 v[6:7], v53 offset0:132 offset1:165
	ds_read2_b32 v[8:9], v53 offset0:198 offset1:231
	s_ashr_i32 s11, s10, 31
	s_waitcnt lgkmcnt(0)
	v_cvt_pk_bf16_f32 v2, v2, v3
	v_cvt_pk_bf16_f32 v3, v4, v5
	v_cvt_pk_bf16_f32 v4, v6, v7
	v_add_u32_e32 v6, s8, v52
	v_ashrrev_i32_e32 v7, 31, v6
	v_lshl_add_u64 v[10:11], s[10:11], 1, v[44:45]
	v_lshlrev_b64 v[6:7], 11, v[6:7]
	v_cvt_pk_bf16_f32 v5, v8, v9
	v_lshl_add_u64 v[6:7], v[10:11], 0, v[6:7]
	global_store_dwordx4 v[6:7], v[2:5], off nt
	ds_read2_b32 v[2:3], v54 offset1:33
	ds_read2_b32 v[4:5], v54 offset0:66 offset1:99
	ds_read2_b32 v[6:7], v54 offset0:132 offset1:165
	ds_read2_b32 v[8:9], v54 offset0:198 offset1:231
	s_add_i32 s27, s27, s33
	s_waitcnt lgkmcnt(0)
	v_cvt_pk_bf16_f32 v2, v2, v3
	v_cvt_pk_bf16_f32 v3, v4, v5
	v_cvt_pk_bf16_f32 v4, v6, v7
	v_add_u32_e32 v6, s8, v1
	v_ashrrev_i32_e32 v7, 31, v6
	v_lshlrev_b64 v[6:7], 11, v[6:7]
	v_cvt_pk_bf16_f32 v5, v8, v9
	v_lshl_add_u64 v[6:7], v[10:11], 0, v[6:7]
	global_store_dwordx4 v[6:7], v[2:5], off nt
	ds_read2_b32 v[2:3], v55 offset1:33
	ds_read2_b32 v[4:5], v55 offset0:66 offset1:99
	ds_read2_b32 v[6:7], v55 offset0:132 offset1:165
	ds_read2_b32 v[8:9], v55 offset0:198 offset1:231
	s_add_i32 s4, s4, s3
	s_waitcnt lgkmcnt(0)
	v_cvt_pk_bf16_f32 v2, v2, v3
	v_cvt_pk_bf16_f32 v3, v4, v5
	v_cvt_pk_bf16_f32 v4, v6, v7
	v_add_u32_e32 v6, s8, v50
	v_ashrrev_i32_e32 v7, 31, v6
	v_lshlrev_b64 v[6:7], 11, v[6:7]
	v_cvt_pk_bf16_f32 v5, v8, v9
	v_lshl_add_u64 v[6:7], v[10:11], 0, v[6:7]
	global_store_dwordx4 v[6:7], v[2:5], off nt
	ds_read2_b32 v[2:3], v56 offset1:33
	ds_read2_b32 v[4:5], v56 offset0:66 offset1:99
	ds_read2_b32 v[6:7], v56 offset0:132 offset1:165
	ds_read2_b32 v[8:9], v56 offset0:198 offset1:231
	s_cmpk_lt_i32 s27, 0x180
	s_waitcnt lgkmcnt(0)
	v_cvt_pk_bf16_f32 v2, v2, v3
	v_cvt_pk_bf16_f32 v3, v4, v5
	v_cvt_pk_bf16_f32 v4, v6, v7
	v_add_u32_e32 v6, s8, v51
	v_ashrrev_i32_e32 v7, 31, v6
	v_lshlrev_b64 v[6:7], 11, v[6:7]
	v_cvt_pk_bf16_f32 v5, v8, v9
	v_lshl_add_u64 v[6:7], v[10:11], 0, v[6:7]
	global_store_dwordx4 v[6:7], v[2:5], off nt
	s_waitcnt lgkmcnt(0)
	s_cbranch_scc0 .LBB0_147

.LBB0_150:
	s_mul_hi_i32 s0, s27, 0x2aaaaaab
	s_lshr_b32 s1, s0, 31
	s_ashr_i32 s0, s0, 3
	s_add_i32 s0, s0, s1
	s_mul_i32 s1, s0, 0xfffffa00
	s_lshl_b32 s8, s0, 6
	s_add_i32 s10, s4, s1
	v_or_b32_e32 v29, s8, v52
	s_ashr_i32 s11, s10, 31
	v_lshl_add_u64 v[6:7], s[10:11], 2, v[2:3]
	v_or_b32_e32 v8, 8, v29
	v_mad_i64_i32 v[30:31], s[10:11], v29, s20, v[6:7]
	v_mad_i64_i32 v[32:33], s[10:11], v8, s20, v[6:7]
	v_or_b32_e32 v35, 32, v29
	global_load_dwordx4 v[8:11], v[30:31], off nt
	global_load_dwordx4 v[12:15], v[32:33], off nt
	v_or_b32_e32 v30, 16, v29
	v_or_b32_e32 v32, 24, v29
	v_mad_i64_i32 v[46:47], s[10:11], v35, s20, v[6:7]
	v_or_b32_e32 v35, 40, v29
	v_mad_i64_i32 v[30:31], s[10:11], v30, s20, v[6:7]
	v_mad_i64_i32 v[42:43], s[10:11], v32, s20, v[6:7]
	v_mad_i64_i32 v[62:63], s[10:11], v35, s20, v[6:7]
	global_load_dwordx4 v[30:33], v[30:31], off nt
	s_nop 0
	global_load_dwordx4 v[42:45], v[42:43], off nt
	s_nop 0
	global_load_dwordx4 v[46:49], v[46:47], off nt
	s_nop 0
	global_load_dwordx4 v[62:65], v[62:63], off nt
	v_or_b32_e32 v35, 48, v29
	v_mad_i64_i32 v[66:67], s[10:11], v35, s20, v[6:7]
	global_load_dwordx4 v[66:69], v[66:67], off nt
	v_or_b32_e32 v29, 56, v29
	v_mad_i64_i32 v[6:7], s[10:11], v29, s20, v[6:7]
	global_load_dwordx4 v[70:73], v[6:7], off nt
	v_add_u32_e32 v7, s4, v52
	v_add_u32_e32 v6, s1, v7
	v_mul_hi_i32 v6, v6, s5
	v_lshrrev_b32_e32 v29, 31, v6
	v_ashrrev_i32_e32 v6, 5, v6
	v_add_u32_e32 v6, v6, v29
	v_mul_lo_u32 v29, v6, s21
	s_mulk_i32 s0, 0x600
	v_subrev_u32_e32 v29, s0, v29
	s_waitcnt vmcnt(0)
	ds_write2_b32 v57, v8, v9 offset1:1
	ds_write2_b32 v57, v10, v11 offset0:2 offset1:3
	ds_write2_b32 v58, v12, v13 offset1:1
	ds_write2_b32 v58, v14, v15 offset0:2 offset1:3
	ds_write2_b32 v59, v30, v31 offset1:1
	ds_write2_b32 v59, v32, v33 offset0:2 offset1:3
	ds_write2_b32 v60, v42, v43 offset1:1
	ds_write2_b32 v60, v44, v45 offset0:2 offset1:3
	ds_write2_b32 v20, v46, v47 offset1:1
	ds_write2_b32 v21, v48, v49 offset1:1
	ds_write2_b32 v22, v62, v63 offset1:1
	ds_write2_b32 v23, v64, v65 offset1:1
	ds_write2_b32 v24, v66, v67 offset1:1
	ds_write2_b32 v25, v68, v69 offset1:1
	ds_write2_b32 v26, v70, v71 offset1:1
	ds_write2_b32 v27, v72, v73 offset1:1
	s_waitcnt lgkmcnt(0)
	ds_read2_b32 v[8:9], v53 offset1:33
	ds_read2_b32 v[10:11], v53 offset0:66 offset1:99
	ds_read2_b32 v[12:13], v53 offset0:132 offset1:165
	ds_read2_b32 v[14:15], v53 offset0:198 offset1:231
	v_add_u32_e32 v30, v7, v29
	v_cmp_lt_i32_e32 vcc, s24, v30
	s_and_saveexec_b64 s[10:11], vcc
	s_xor_b64 s[10:11], exec, s[10:11]
	v_lshlrev_b32_e32 v7, 6, v6
	v_and_b32_e32 v7, 0xffffff00, v7
	v_lshl_add_u32 v29, v30, 2, v28
	v_lshlrev_b32_e32 v6, 5, v6
	v_add_u32_e32 v7, v16, v7
	v_and_b32_e32 v29, 0x7fffff80, v29
	v_and_or_b32 v6, v6, s25, v7
	v_add_u32_e32 v29, v6, v29
	s_andn2_saveexec_b64 s[10:11], s[10:11]
	v_lshl_add_u32 v6, v6, 6, s0
	v_sub_u32_e32 v29, v7, v6
	s_or_b64 exec, exec, s[10:11]
	s_ashr_i32 s9, s8, 31
	v_lshl_add_u64 v[6:7], s[8:9], 1, v[4:5]
	s_waitcnt lgkmcnt(0)
	v_cvt_pk_bf16_f32 v8, v8, v9
	v_cvt_pk_bf16_f32 v9, v10, v11
	v_cvt_pk_bf16_f32 v10, v12, v13
	v_cvt_pk_bf16_f32 v11, v14, v15
	v_mad_i64_i32 v[12:13], s[8:9], v29, s26, v[6:7]
	v_add_u32_e32 v31, s4, v1
	global_store_dwordx4 v[12:13], v[8:11], off nt
	v_add_u32_e32 v29, s1, v31
	ds_read2_b32 v[8:9], v54 offset1:33
	ds_read2_b32 v[10:11], v54 offset0:66 offset1:99
	ds_read2_b32 v[12:13], v54 offset0:132 offset1:165
	ds_read2_b32 v[14:15], v54 offset0:198 offset1:231
	v_mul_hi_i32 v29, v29, s5
	v_lshrrev_b32_e32 v30, 31, v29
	v_ashrrev_i32_e32 v29, 5, v29
	v_add_u32_e32 v30, v29, v30
	v_mul_lo_u32 v29, v30, s21
	v_subrev_u32_e32 v29, s0, v29
	v_add_u32_e32 v32, v31, v29
	v_cmp_lt_i32_e32 vcc, s24, v32
	s_and_saveexec_b64 s[8:9], vcc
	s_xor_b64 s[8:9], exec, s[8:9]
	v_lshlrev_b32_e32 v29, 6, v30
	v_and_b32_e32 v29, 0xffffff00, v29
	v_lshl_add_u32 v31, v32, 2, v28
	v_lshlrev_b32_e32 v30, 5, v30
	v_add_u32_e32 v29, v17, v29
	v_and_b32_e32 v31, 0x7fffff80, v31
	v_and_or_b32 v29, v30, s25, v29
	v_add_u32_e32 v29, v29, v31
	s_andn2_saveexec_b64 s[8:9], s[8:9]
	v_lshl_add_u32 v29, v30, 6, s0
	v_sub_u32_e32 v29, v31, v29
	s_or_b64 exec, exec, s[8:9]
	s_waitcnt lgkmcnt(0)
	v_cvt_pk_bf16_f32 v8, v8, v9
	v_cvt_pk_bf16_f32 v9, v10, v11
	v_cvt_pk_bf16_f32 v10, v12, v13
	v_cvt_pk_bf16_f32 v11, v14, v15
	v_mad_i64_i32 v[12:13], s[8:9], v29, s26, v[6:7]
	v_add_u32_e32 v31, s4, v50
	global_store_dwordx4 v[12:13], v[8:11], off nt
	v_add_u32_e32 v29, s1, v31
	ds_read2_b32 v[8:9], v55 offset1:33
	ds_read2_b32 v[10:11], v55 offset0:66 offset1:99
	ds_read2_b32 v[12:13], v55 offset0:132 offset1:165
	ds_read2_b32 v[14:15], v55 offset0:198 offset1:231
	v_mul_hi_i32 v29, v29, s5
	v_lshrrev_b32_e32 v30, 31, v29
	v_ashrrev_i32_e32 v29, 5, v29
	v_add_u32_e32 v30, v29, v30
	v_mul_lo_u32 v29, v30, s21
	v_subrev_u32_e32 v29, s0, v29
	v_add_u32_e32 v32, v31, v29
	v_cmp_lt_i32_e32 vcc, s24, v32
	s_and_saveexec_b64 s[8:9], vcc
	s_xor_b64 s[8:9], exec, s[8:9]
	v_lshlrev_b32_e32 v29, 6, v30
	v_and_b32_e32 v29, 0xffffff00, v29
	v_lshl_add_u32 v31, v32, 2, v28
	v_lshlrev_b32_e32 v30, 5, v30
	v_add_u32_e32 v29, v18, v29
	v_and_b32_e32 v31, 0x7fffff80, v31
	v_and_or_b32 v29, v30, s25, v29
	v_add_u32_e32 v29, v29, v31
	s_andn2_saveexec_b64 s[8:9], s[8:9]
	v_lshl_add_u32 v29, v30, 6, s0
	v_sub_u32_e32 v29, v31, v29
	s_or_b64 exec, exec, s[8:9]
	s_waitcnt lgkmcnt(0)
	v_cvt_pk_bf16_f32 v8, v8, v9
	v_cvt_pk_bf16_f32 v9, v10, v11
	v_cvt_pk_bf16_f32 v10, v12, v13
	v_cvt_pk_bf16_f32 v11, v14, v15
	v_mad_i64_i32 v[12:13], s[8:9], v29, s26, v[6:7]
	v_add_u32_e32 v31, s4, v51
	global_store_dwordx4 v[12:13], v[8:11], off nt
	v_add_u32_e32 v29, s1, v31
	ds_read2_b32 v[8:9], v56 offset1:33
	ds_read2_b32 v[10:11], v56 offset0:66 offset1:99
	ds_read2_b32 v[12:13], v56 offset0:132 offset1:165
	ds_read2_b32 v[14:15], v56 offset0:198 offset1:231
	v_mul_hi_i32 v29, v29, s5
	v_lshrrev_b32_e32 v30, 31, v29
	v_ashrrev_i32_e32 v29, 5, v29
	v_add_u32_e32 v30, v29, v30
	v_mul_lo_u32 v29, v30, s21
	v_subrev_u32_e32 v29, s0, v29
	v_add_u32_e32 v32, v31, v29
	v_cmp_lt_i32_e32 vcc, s24, v32
	s_and_saveexec_b64 s[8:9], vcc
	s_xor_b64 s[8:9], exec, s[8:9]
	v_lshlrev_b32_e32 v29, 6, v30
	v_and_b32_e32 v29, 0xffffff00, v29
	v_lshl_add_u32 v31, v32, 2, v28
	v_lshlrev_b32_e32 v30, 5, v30
	v_add_u32_e32 v29, v19, v29
	v_and_b32_e32 v31, 0x7fffff80, v31
	v_and_or_b32 v29, v30, s25, v29
	v_add_u32_e32 v29, v29, v31
	s_andn2_saveexec_b64 s[8:9], s[8:9]
	s_cbranch_execz .LBB0_149
	v_lshl_add_u32 v29, v30, 6, s0
	v_sub_u32_e32 v29, v31, v29
	s_branch .LBB0_149

.LBB0_168:
	s_or_b64 exec, exec, s[10:11]
	s_waitcnt vmcnt(0)
	ds_write2_b32 v57, v6, v7 offset1:1
	ds_write2_b32 v57, v8, v9 offset0:2 offset1:3
	ds_write2_b32 v58, v2, v3 offset1:1
	ds_write2_b32 v58, v4, v5 offset0:2 offset1:3
	ds_write2_b32 v59, v14, v15 offset1:1
	ds_write2_b32 v59, v16, v17 offset0:2 offset1:3
	ds_write2_b32 v60, v10, v11 offset1:1
	ds_write2_b32 v60, v12, v13 offset0:2 offset1:3
	v_add_u32_e32 v2, 0x1080, v57
	ds_write2_b32 v2, v22, v23 offset1:1
	v_add_u32_e32 v2, 0x1088, v57
	ds_write2_b32 v2, v24, v25 offset1:1
	v_add_u32_e32 v2, 0x14a0, v57
	ds_write2_b32 v2, v18, v19 offset1:1
	v_add_u32_e32 v2, 0x14a8, v57
	ds_write2_b32 v2, v20, v21 offset1:1
	v_add_u32_e32 v2, 0x18c0, v57
	ds_write2_b32 v2, v30, v31 offset1:1
	v_add_u32_e32 v2, 0x18c8, v57
	ds_write2_b32 v2, v32, v33 offset1:1
	v_add_u32_e32 v2, 0x1ce0, v57
	ds_write2_b32 v2, v26, v27 offset1:1
	v_add_u32_e32 v2, 0x1ce8, v57
	ds_write2_b32 v2, v28, v29 offset1:1
	s_waitcnt lgkmcnt(0)
	ds_read2_b32 v[2:3], v53 offset1:33
	ds_read2_b32 v[4:5], v53 offset0:66 offset1:99
	ds_read2_b32 v[6:7], v53 offset0:132 offset1:165
	ds_read2_b32 v[8:9], v53 offset0:198 offset1:231
	s_sub_i32 s0, 0, s1
	s_add_i32 s0, s0, s4
	s_waitcnt lgkmcnt(0)
	v_cvt_pk_bf16_f32 v2, v2, v3
	v_cvt_pk_bf16_f32 v3, v4, v5
	v_cvt_pk_bf16_f32 v4, v6, v7
	v_add_u32_e32 v6, s0, v52
	s_ashr_i32 s9, s8, 31
	v_ashrrev_i32_e32 v7, 31, v6
	v_lshl_add_u64 v[10:11], s[8:9], 1, v[44:45]
	v_lshlrev_b64 v[6:7], 9, v[6:7]
	v_cvt_pk_bf16_f32 v5, v8, v9
	v_lshl_add_u64 v[6:7], v[10:11], 0, v[6:7]
	global_store_dwordx4 v[6:7], v[2:5], off nt
	ds_read2_b32 v[2:3], v54 offset1:33
	ds_read2_b32 v[4:5], v54 offset0:66 offset1:99
	ds_read2_b32 v[6:7], v54 offset0:132 offset1:165
	ds_read2_b32 v[8:9], v54 offset0:198 offset1:231
	s_add_i32 s20, s20, s33
	s_waitcnt lgkmcnt(0)
	v_cvt_pk_bf16_f32 v2, v2, v3
	v_cvt_pk_bf16_f32 v3, v4, v5
	v_cvt_pk_bf16_f32 v4, v6, v7
	v_add_u32_e32 v6, s0, v1
	v_ashrrev_i32_e32 v7, 31, v6
	v_lshlrev_b64 v[6:7], 9, v[6:7]
	v_cvt_pk_bf16_f32 v5, v8, v9
	v_lshl_add_u64 v[6:7], v[10:11], 0, v[6:7]
	global_store_dwordx4 v[6:7], v[2:5], off nt
	ds_read2_b32 v[2:3], v55 offset1:33
	ds_read2_b32 v[4:5], v55 offset0:66 offset1:99
	ds_read2_b32 v[6:7], v55 offset0:132 offset1:165
	ds_read2_b32 v[8:9], v55 offset0:198 offset1:231
	s_add_i32 s4, s4, s3
	s_waitcnt lgkmcnt(0)
	v_cvt_pk_bf16_f32 v2, v2, v3
	v_cvt_pk_bf16_f32 v3, v4, v5
	v_cvt_pk_bf16_f32 v4, v6, v7
	v_add_u32_e32 v6, s0, v50
	v_ashrrev_i32_e32 v7, 31, v6
	v_lshlrev_b64 v[6:7], 9, v[6:7]
	v_cvt_pk_bf16_f32 v5, v8, v9
	v_lshl_add_u64 v[6:7], v[10:11], 0, v[6:7]
	global_store_dwordx4 v[6:7], v[2:5], off nt
	ds_read2_b32 v[2:3], v56 offset1:33
	ds_read2_b32 v[4:5], v56 offset0:66 offset1:99
	ds_read2_b32 v[6:7], v56 offset0:132 offset1:165
	ds_read2_b32 v[8:9], v56 offset0:198 offset1:231
	s_cmpk_lt_i32 s20, 0x100
	s_waitcnt lgkmcnt(0)
	v_cvt_pk_bf16_f32 v2, v2, v3
	v_cvt_pk_bf16_f32 v3, v4, v5
	v_cvt_pk_bf16_f32 v4, v6, v7
	v_add_u32_e32 v6, s0, v51
	v_ashrrev_i32_e32 v7, 31, v6
	v_lshlrev_b64 v[6:7], 9, v[6:7]
	v_cvt_pk_bf16_f32 v5, v8, v9
	v_lshl_add_u64 v[6:7], v[10:11], 0, v[6:7]
	global_store_dwordx4 v[6:7], v[2:5], off nt
	s_waitcnt lgkmcnt(0)
	s_cbranch_scc0 .LBB0_185

.LBB0_187:
	s_or_b64 exec, exec, s[8:9]
	s_waitcnt vmcnt(0)
	ds_write2_b32 v57, v6, v7 offset1:1
	ds_write2_b32 v57, v8, v9 offset0:2 offset1:3
	ds_write2_b32 v58, v2, v3 offset1:1
	ds_write2_b32 v58, v4, v5 offset0:2 offset1:3
	ds_write2_b32 v59, v14, v15 offset1:1
	ds_write2_b32 v59, v16, v17 offset0:2 offset1:3
	ds_write2_b32 v60, v10, v11 offset1:1
	ds_write2_b32 v60, v12, v13 offset0:2 offset1:3
	v_add_u32_e32 v2, 0x1080, v57
	ds_write2_b32 v2, v22, v23 offset1:1
	v_add_u32_e32 v2, 0x1088, v57
	ds_write2_b32 v2, v24, v25 offset1:1
	v_add_u32_e32 v2, 0x14a0, v57
	ds_write2_b32 v2, v18, v19 offset1:1
	v_add_u32_e32 v2, 0x14a8, v57
	ds_write2_b32 v2, v20, v21 offset1:1
	v_add_u32_e32 v2, 0x18c0, v57
	ds_write2_b32 v2, v30, v31 offset1:1
	v_add_u32_e32 v2, 0x18c8, v57
	ds_write2_b32 v2, v32, v33 offset1:1
	v_add_u32_e32 v2, 0x1ce0, v57
	ds_write2_b32 v2, v26, v27 offset1:1
	v_add_u32_e32 v2, 0x1ce8, v57
	ds_write2_b32 v2, v28, v29 offset1:1
	s_waitcnt lgkmcnt(0)
	ds_read2_b32 v[2:3], v53 offset1:33
	ds_read2_b32 v[4:5], v53 offset0:66 offset1:99
	ds_read2_b32 v[6:7], v53 offset0:132 offset1:165
	ds_read2_b32 v[8:9], v53 offset0:198 offset1:231
	s_sub_i32 s0, 0, s1
	s_add_i32 s0, s0, s4
	s_waitcnt lgkmcnt(0)
	v_cvt_pk_bf16_f32 v2, v2, v3
	v_cvt_pk_bf16_f32 v3, v4, v5
	v_cvt_pk_bf16_f32 v4, v6, v7
	v_add_u32_e32 v6, s0, v52
	s_ashr_i32 s7, s6, 31
	v_ashrrev_i32_e32 v7, 31, v6
	v_lshl_add_u64 v[10:11], s[6:7], 1, v[40:41]
	v_lshlrev_b64 v[6:7], 11, v[6:7]
	v_cvt_pk_bf16_f32 v5, v8, v9
	v_lshl_add_u64 v[6:7], v[10:11], 0, v[6:7]
	global_store_dwordx4 v[6:7], v[2:5], off nt
	ds_read2_b32 v[2:3], v54 offset1:33
	ds_read2_b32 v[4:5], v54 offset0:66 offset1:99
	ds_read2_b32 v[6:7], v54 offset0:132 offset1:165
	ds_read2_b32 v[8:9], v54 offset0:198 offset1:231
	s_add_i32 s10, s10, s33
	s_waitcnt lgkmcnt(0)
	v_cvt_pk_bf16_f32 v2, v2, v3
	v_cvt_pk_bf16_f32 v3, v4, v5
	v_cvt_pk_bf16_f32 v4, v6, v7
	v_add_u32_e32 v6, s0, v1
	v_ashrrev_i32_e32 v7, 31, v6
	v_lshlrev_b64 v[6:7], 11, v[6:7]
	v_cvt_pk_bf16_f32 v5, v8, v9
	v_lshl_add_u64 v[6:7], v[10:11], 0, v[6:7]
	global_store_dwordx4 v[6:7], v[2:5], off nt
	ds_read2_b32 v[2:3], v55 offset1:33
	ds_read2_b32 v[4:5], v55 offset0:66 offset1:99
	ds_read2_b32 v[6:7], v55 offset0:132 offset1:165
	ds_read2_b32 v[8:9], v55 offset0:198 offset1:231
	s_add_i32 s4, s4, s3
	s_waitcnt lgkmcnt(0)
	v_cvt_pk_bf16_f32 v2, v2, v3
	v_cvt_pk_bf16_f32 v3, v4, v5
	v_cvt_pk_bf16_f32 v4, v6, v7
	v_add_u32_e32 v6, s0, v50
	v_ashrrev_i32_e32 v7, 31, v6
	v_lshlrev_b64 v[6:7], 11, v[6:7]
	v_cvt_pk_bf16_f32 v5, v8, v9
	v_lshl_add_u64 v[6:7], v[10:11], 0, v[6:7]
	global_store_dwordx4 v[6:7], v[2:5], off nt
	ds_read2_b32 v[2:3], v56 offset1:33
	ds_read2_b32 v[4:5], v56 offset0:66 offset1:99
	ds_read2_b32 v[6:7], v56 offset0:132 offset1:165
	ds_read2_b32 v[8:9], v56 offset0:198 offset1:231
	s_cmpk_gt_i32 s10, 0x1ff
	s_waitcnt lgkmcnt(0)
	v_cvt_pk_bf16_f32 v2, v2, v3
	v_cvt_pk_bf16_f32 v3, v4, v5
	v_cvt_pk_bf16_f32 v4, v6, v7
	v_add_u32_e32 v6, s0, v51
	v_ashrrev_i32_e32 v7, 31, v6
	v_lshlrev_b64 v[6:7], 11, v[6:7]
	v_cvt_pk_bf16_f32 v5, v8, v9
	v_lshl_add_u64 v[6:7], v[10:11], 0, v[6:7]
	global_store_dwordx4 v[6:7], v[2:5], off nt
	s_waitcnt lgkmcnt(0)
	s_cbranch_scc1 .LBB0_204

.LBB0_213:
	s_mul_hi_i32 s0, s18, 0x2aaaaaab
	s_lshr_b32 s1, s0, 31
	s_ashr_i32 s0, s0, 8
	s_add_i32 s8, s0, s1
	s_mul_i32 s0, s8, 0xfffffa00
	s_add_i32 s21, s18, s0
	s_lshr_b32 s0, s21, 22
	s_and_b32 s0, s0, 0x1ff
	s_add_i32 s22, s21, s0
	s_and_b32 s0, s22, 0xfe00
	s_sub_i32 s0, s21, s0
	s_sext_i32_i16 s1, s0
	s_bfe_u32 s1, s1, 0x5001a
	s_add_i32 s1, s0, s1
	s_sext_i32_i16 s6, s1
	s_and_b32 s1, s1, 0xffe0
	s_lshl_b32 s20, s6, 1
	s_sub_i32 s0, s0, s1
	s_andn2_b32 s20, s20, 63
	s_sext_i32_i16 s19, s0
	s_lshl_b32 s6, s19, 5
	v_or_b32_e32 v16, s20, v52
	s_mov_b64 s[10:11], -1
	s_cmpk_gt_i32 s21, 0x3ff
	v_ashrrev_i32_e32 v17, 31, v16
	v_or_b32_e32 v14, 8, v16
	v_or_b32_e32 v12, 16, v16
	v_or_b32_e32 v10, 24, v16
	v_or_b32_e32 v8, 32, v16
	v_or_b32_e32 v6, 40, v16
	v_or_b32_e32 v4, 48, v16
	v_or_b32_e32 v2, 56, v16
	s_cbranch_scc0 .LBB0_215
	s_ashr_i32 s9, s8, 31
	s_lshl_b64 s[0:1], s[8:9], 20
	s_lshl_b64 s[10:11], s[8:9], 22
	s_add_u32 s9, s34, s10
	s_addc_u32 s10, s35, s11
	s_add_u32 s11, s5, s0
	s_addc_u32 s23, s16, s1
	s_ashr_i32 s7, s6, 31
	s_lshl_b64 s[0:1], s[6:7], 2
	s_add_u32 s0, s9, s0
	s_addc_u32 s1, s10, s1
	v_lshl_add_u64 v[48:49], v[36:37], 2, s[0:1]
	v_lshlrev_b64 v[28:29], 12, v[16:17]
	v_ashrrev_i32_e32 v15, 31, v14
	v_lshl_add_u64 v[40:41], v[48:49], 0, v[28:29]
	v_lshlrev_b64 v[28:29], 12, v[14:15]
	v_ashrrev_i32_e32 v13, 31, v12
	v_lshl_add_u64 v[42:43], v[48:49], 0, v[28:29]
	global_load_dwordx4 v[28:31], v[40:41], off nt
	global_load_dwordx4 v[32:35], v[42:43], off nt
	v_lshlrev_b64 v[40:41], 12, v[12:13]
	v_ashrrev_i32_e32 v11, 31, v10
	v_lshl_add_u64 v[62:63], v[48:49], 0, v[40:41]
	v_lshlrev_b64 v[40:41], 12, v[10:11]
	v_ashrrev_i32_e32 v9, 31, v8
	v_lshl_add_u64 v[64:65], v[48:49], 0, v[40:41]
	global_load_dwordx4 v[40:43], v[62:63], off nt
	global_load_dwordx4 v[44:47], v[64:65], off nt
	v_lshlrev_b64 v[62:63], 12, v[8:9]
	v_ashrrev_i32_e32 v7, 31, v6
	v_lshl_add_u64 v[70:71], v[48:49], 0, v[62:63]
	v_lshlrev_b64 v[62:63], 12, v[6:7]
	v_lshl_add_u64 v[72:73], v[48:49], 0, v[62:63]
	global_load_dwordx4 v[62:65], v[70:71], off nt
	global_load_dwordx4 v[66:69], v[72:73], off nt
	v_ashrrev_i32_e32 v5, 31, v4
	v_lshlrev_b64 v[70:71], 12, v[4:5]
	v_lshl_add_u64 v[70:71], v[48:49], 0, v[70:71]
	v_ashrrev_i32_e32 v3, 31, v2
	global_load_dwordx4 v[70:73], v[70:71], off nt
	v_lshlrev_b64 v[74:75], 12, v[2:3]
	v_lshl_add_u64 v[48:49], v[48:49], 0, v[74:75]
	global_load_dwordx4 v[74:77], v[48:49], off nt
	v_mov_b32_e32 v48, 0
	v_mov_b32_e32 v49, 0
	s_ashr_i32 s1, s20, 31
	v_or_b32_e32 v78, s6, v52
	s_add_u32 s0, s11, s20
	v_ashrrev_i32_e32 v79, 31, v78
	s_addc_u32 s1, s23, s1
	v_lshlrev_b64 v[78:79], 10, v[78:79]
	v_mov_b32_e32 v80, 0
	v_mov_b32_e32 v81, 0
	s_waitcnt vmcnt(0)
	ds_write2_b32 v57, v28, v29 offset1:1
	ds_write2_b32 v57, v30, v31 offset0:2 offset1:3
	ds_write2_b32 v58, v32, v33 offset1:1
	ds_write2_b32 v58, v34, v35 offset0:2 offset1:3
	ds_write2_b32 v59, v40, v41 offset1:1
	ds_write2_b32 v59, v42, v43 offset0:2 offset1:3
	ds_write2_b32 v60, v44, v45 offset1:1
	ds_write2_b32 v60, v46, v47 offset0:2 offset1:3
	ds_write2_b32 v18, v62, v63 offset1:1
	ds_write2_b32 v19, v64, v65 offset1:1
	ds_write2_b32 v20, v66, v67 offset1:1
	ds_write2_b32 v21, v68, v69 offset1:1
	ds_write2_b32 v22, v70, v71 offset1:1
	ds_write2_b32 v23, v72, v73 offset1:1
	ds_write2_b32 v24, v74, v75 offset1:1
	ds_write2_b32 v25, v76, v77 offset1:1
	s_waitcnt lgkmcnt(0)
	ds_read2_b32 v[28:29], v53 offset1:33
	ds_read2_b32 v[30:31], v53 offset0:66 offset1:99
	ds_read2_b32 v[32:33], v53 offset0:132 offset1:165
	ds_read2_b32 v[34:35], v53 offset0:198 offset1:231
	s_waitcnt lgkmcnt(0)
	v_mul_f32_e32 v7, 0x43000000, v30
	v_mul_f32_e32 v3, 0x43000000, v28
	v_mul_f32_e32 v5, 0x43000000, v29
	v_mul_f32_e32 v11, 0x43000000, v32
	v_mul_f32_e32 v13, 0x43000000, v33
	v_med3_f32 v3, v3, s17, v26
	v_med3_f32 v5, v5, s17, v26
	v_med3_f32 v11, v11, s17, v26
	v_med3_f32 v13, v13, s17, v26
	v_cvt_pk_fp8_f32 v48, v3, v5
	v_cvt_pk_fp8_f32 v49, v11, v13
	v_mul_f32_e32 v9, 0x43000000, v31
	v_mul_f32_e32 v15, 0x43000000, v34
	v_mul_f32_e32 v27, 0x43000000, v35
	v_med3_f32 v7, v7, s17, v26
	v_med3_f32 v9, v9, s17, v26
	v_med3_f32 v3, v15, s17, v26
	v_med3_f32 v5, v27, s17, v26
	v_cvt_pk_fp8_f32 v48, v7, v9 op_sel:[0,0,1]
	v_cvt_pk_fp8_f32 v49, v3, v5 op_sel:[0,0,1]
	v_lshl_add_u64 v[28:29], s[0:1], 0, v[38:39]
	v_lshl_add_u64 v[30:31], v[28:29], 0, v[78:79]
	global_store_dwordx2 v[30:31], v[48:49], off nt
	ds_read2_b32 v[30:31], v54 offset1:33
	ds_read2_b32 v[32:33], v54 offset0:66 offset1:99
	ds_read2_b32 v[34:35], v54 offset0:132 offset1:165
	ds_read2_b32 v[40:41], v54 offset0:198 offset1:231
	s_waitcnt lgkmcnt(0)
	v_mul_f32_e32 v7, 0x43000000, v32
	v_mul_f32_e32 v3, 0x43000000, v30
	v_mul_f32_e32 v5, 0x43000000, v31
	v_mul_f32_e32 v11, 0x43000000, v34
	v_mul_f32_e32 v13, 0x43000000, v35
	v_med3_f32 v3, v3, s17, v26
	v_med3_f32 v5, v5, s17, v26
	v_med3_f32 v11, v11, s17, v26
	v_med3_f32 v13, v13, s17, v26
	v_cvt_pk_fp8_f32 v80, v3, v5
	v_cvt_pk_fp8_f32 v81, v11, v13
	v_mul_f32_e32 v9, 0x43000000, v33
	v_mul_f32_e32 v15, 0x43000000, v40
	v_mul_f32_e32 v27, 0x43000000, v41
	v_med3_f32 v7, v7, s17, v26
	v_med3_f32 v9, v9, s17, v26
	v_med3_f32 v3, v15, s17, v26
	v_med3_f32 v5, v27, s17, v26
	v_cvt_pk_fp8_f32 v80, v7, v9 op_sel:[0,0,1]
	v_cvt_pk_fp8_f32 v81, v3, v5 op_sel:[0,0,1]
	v_or_b32_e32 v30, s6, v1
	v_ashrrev_i32_e32 v31, 31, v30
	v_lshlrev_b64 v[30:31], 10, v[30:31]
	v_lshl_add_u64 v[30:31], v[28:29], 0, v[30:31]
	global_store_dwordx2 v[30:31], v[80:81], off nt
	ds_read2_b32 v[30:31], v55 offset1:33
	ds_read2_b32 v[32:33], v55 offset0:66 offset1:99
	ds_read2_b32 v[34:35], v55 offset0:198 offset1:231
	s_waitcnt lgkmcnt(0)
	v_mul_f32_e32 v3, 0x43000000, v30
	v_mul_f32_e32 v5, 0x43000000, v31
	v_mul_f32_e32 v7, 0x43000000, v32
	v_mul_f32_e32 v9, 0x43000000, v33
	v_med3_f32 v3, v3, s17, v26
	v_med3_f32 v5, v5, s17, v26
	v_mov_b32_e32 v30, 0
	ds_read2_b32 v[32:33], v55 offset0:132 offset1:165
	v_cvt_pk_fp8_f32 v30, v3, v5
	v_med3_f32 v3, v7, s17, v26
	v_med3_f32 v5, v9, s17, v26
	v_mov_b32_e32 v31, 0
	v_cvt_pk_fp8_f32 v30, v3, v5 op_sel:[0,0,1]
	s_waitcnt lgkmcnt(0)
	v_mul_f32_e32 v3, 0x43000000, v32
	v_mul_f32_e32 v5, 0x43000000, v33
	v_med3_f32 v3, v3, s17, v26
	v_med3_f32 v5, v5, s17, v26
	v_cvt_pk_fp8_f32 v31, v3, v5
	v_mul_f32_e32 v7, 0x43000000, v34
	v_mul_f32_e32 v3, 0x43000000, v35
	v_med3_f32 v5, v7, s17, v26
	v_med3_f32 v3, v3, s17, v26
	v_cvt_pk_fp8_f32 v31, v5, v3 op_sel:[0,0,1]
	v_or_b32_e32 v32, s6, v50
	v_ashrrev_i32_e32 v33, 31, v32
	v_lshlrev_b64 v[32:33], 10, v[32:33]
	v_lshl_add_u64 v[32:33], v[28:29], 0, v[32:33]
	global_store_dwordx2 v[32:33], v[30:31], off nt
	ds_read2_b32 v[30:31], v56 offset1:33
	ds_read2_b32 v[32:33], v56 offset0:66 offset1:99
	ds_read2_b32 v[34:35], v56 offset0:198 offset1:231
	s_waitcnt lgkmcnt(0)
	v_mul_f32_e32 v3, 0x43000000, v30
	v_mul_f32_e32 v5, 0x43000000, v31
	v_mul_f32_e32 v7, 0x43000000, v32
	v_mul_f32_e32 v9, 0x43000000, v33
	v_med3_f32 v3, v3, s17, v26
	v_med3_f32 v5, v5, s17, v26
	v_mov_b32_e32 v30, 0
	ds_read2_b32 v[32:33], v56 offset0:132 offset1:165
	v_cvt_pk_fp8_f32 v30, v3, v5
	v_med3_f32 v3, v7, s17, v26
	v_med3_f32 v5, v9, s17, v26
	v_mov_b32_e32 v31, 0
	v_cvt_pk_fp8_f32 v30, v3, v5 op_sel:[0,0,1]
	s_waitcnt lgkmcnt(0)
	v_mul_f32_e32 v3, 0x43000000, v32
	v_mul_f32_e32 v5, 0x43000000, v33
	v_med3_f32 v3, v3, s17, v26
	v_med3_f32 v5, v5, s17, v26
	v_cvt_pk_fp8_f32 v31, v3, v5
	v_mul_f32_e32 v7, 0x43000000, v34
	v_mul_f32_e32 v3, 0x43000000, v35
	v_med3_f32 v5, v7, s17, v26
	v_med3_f32 v3, v3, s17, v26
	v_cvt_pk_fp8_f32 v31, v5, v3 op_sel:[0,0,1]
	v_or_b32_e32 v32, s6, v51
	v_ashrrev_i32_e32 v33, 31, v32
	v_lshlrev_b64 v[32:33], 10, v[32:33]
	v_lshl_add_u64 v[28:29], v[28:29], 0, v[32:33]
	global_store_dwordx2 v[28:29], v[30:31], off nt
	s_waitcnt lgkmcnt(0)
	s_cbranch_execnz .LBB0_212
	s_branch .LBB0_216

.LBB0_216:
	s_sext_i32_i16 s0, s22
	s_lshr_b32 s10, s0, 9
	s_addk_i32 s21, 0x1ff
	s_cmpk_lt_u32 s21, 0x3ff
	s_cselect_b32 s7, s13, s15
	s_cselect_b32 s11, s12, s14
	s_ashr_i32 s9, s8, 31
	s_lshl_b64 s[0:1], s[8:9], 22
	s_add_u32 s11, s11, s0
	s_addc_u32 s21, s7, s1
	s_lshl_b64 s[0:1], s[8:9], 21
	s_add_u32 s8, s3, s0
	s_addc_u32 s9, s4, s1
	s_ashr_i32 s7, s6, 31
	s_lshl_b64 s[0:1], s[6:7], 2
	s_add_u32 s0, s11, s0
	s_addc_u32 s1, s21, s1
	v_ashrrev_i32_e32 v15, 31, v14
	v_ashrrev_i32_e32 v13, 31, v12
	v_ashrrev_i32_e32 v11, 31, v10
	v_ashrrev_i32_e32 v9, 31, v8
	v_lshl_add_u64 v[48:49], v[36:37], 2, s[0:1]
	v_lshlrev_b64 v[16:17], 12, v[16:17]
	v_lshlrev_b64 v[14:15], 12, v[14:15]
	v_lshlrev_b64 v[12:13], 12, v[12:13]
	v_lshlrev_b64 v[10:11], 12, v[10:11]
	v_lshlrev_b64 v[8:9], 12, v[8:9]
	v_ashrrev_i32_e32 v7, 31, v6
	v_lshl_add_u64 v[32:33], v[48:49], 0, v[16:17]
	v_lshl_add_u64 v[34:35], v[48:49], 0, v[14:15]
	v_lshl_add_u64 v[40:41], v[48:49], 0, v[12:13]
	v_lshl_add_u64 v[42:43], v[48:49], 0, v[10:11]
	v_lshl_add_u64 v[44:45], v[48:49], 0, v[8:9]
	v_lshlrev_b64 v[6:7], 12, v[6:7]
	global_load_dwordx4 v[14:17], v[32:33], off nt
	global_load_dwordx4 v[28:31], v[34:35], off nt
	global_load_dwordx4 v[10:13], v[40:41], off nt
	s_nop 0
	global_load_dwordx4 v[32:35], v[42:43], off nt
	v_lshl_add_u64 v[46:47], v[48:49], 0, v[6:7]
	global_load_dwordx4 v[6:9], v[44:45], off nt
	global_load_dwordx4 v[40:43], v[46:47], off nt
	v_ashrrev_i32_e32 v5, 31, v4
	v_lshlrev_b64 v[4:5], 12, v[4:5]
	v_lshl_add_u64 v[4:5], v[48:49], 0, v[4:5]
	v_ashrrev_i32_e32 v3, 31, v2
	global_load_dwordx4 v[44:47], v[4:5], off nt
	v_lshlrev_b64 v[2:3], 12, v[2:3]
	v_lshl_add_u64 v[2:3], v[48:49], 0, v[2:3]
	global_load_dwordx4 v[2:5], v[2:3], off nt
	s_sext_i32_i16 s0, s10
	s_lshl_b32 s7, s0, 7
	s_ashr_i32 s1, s20, 31
	v_mov_b32_e32 v48, 0
	v_mov_b32_e32 v49, 0
	s_add_u32 s0, s8, s20
	s_addc_u32 s1, s9, s1
	s_lshl_b32 s8, s19, 6
	v_lshl_add_u64 v[62:63], s[0:1], 0, v[38:39]
	s_and_b32 s0, s8, 0xffffff00
	s_and_b32 s6, s6, 0x60
	s_add_i32 s0, s0, s7
	s_or_b32 s0, s0, s6
	s_waitcnt vmcnt(0)
	ds_write2_b32 v57, v14, v15 offset1:1
	ds_write2_b32 v57, v16, v17 offset0:2 offset1:3
	ds_write2_b32 v58, v28, v29 offset1:1
	ds_write2_b32 v58, v30, v31 offset0:2 offset1:3
	ds_write2_b32 v59, v10, v11 offset1:1
	ds_write2_b32 v59, v12, v13 offset0:2 offset1:3
	ds_write2_b32 v60, v32, v33 offset1:1
	ds_write2_b32 v60, v34, v35 offset0:2 offset1:3
	ds_write2_b32 v18, v6, v7 offset1:1
	ds_write2_b32 v19, v8, v9 offset1:1
	ds_write2_b32 v20, v40, v41 offset1:1
	ds_write2_b32 v21, v42, v43 offset1:1
	ds_write2_b32 v22, v44, v45 offset1:1
	ds_write2_b32 v23, v46, v47 offset1:1
	ds_write2_b32 v24, v2, v3 offset1:1
	ds_write2_b32 v25, v4, v5 offset1:1
	s_waitcnt lgkmcnt(0)
	ds_read2_b32 v[2:3], v53 offset1:33
	ds_read2_b32 v[6:7], v53 offset0:66 offset1:99
	ds_read2_b32 v[8:9], v53 offset0:132 offset1:165
	ds_read2_b32 v[10:11], v53 offset0:198 offset1:231
	v_or_b32_e32 v4, s0, v52
	s_waitcnt lgkmcnt(0)
	v_mul_f32_e32 v5, 0x42800000, v6
	v_mul_f32_e32 v2, 0x42800000, v2
	v_mul_f32_e32 v3, 0x42800000, v3
	v_mul_f32_e32 v6, 0x42800000, v7
	v_mul_f32_e32 v7, 0x42800000, v8
	v_mul_f32_e32 v8, 0x42800000, v9
	v_med3_f32 v2, v2, s17, v26
	v_med3_f32 v3, v3, s17, v26
	v_med3_f32 v7, v7, s17, v26
	v_med3_f32 v8, v8, s17, v26
	v_cvt_pk_fp8_f32 v48, v2, v3
	v_cvt_pk_fp8_f32 v49, v7, v8
	v_mul_f32_e32 v9, 0x42800000, v10
	v_mul_f32_e32 v10, 0x42800000, v11
	v_med3_f32 v5, v5, s17, v26
	v_med3_f32 v6, v6, s17, v26
	v_med3_f32 v2, v9, s17, v26
	v_med3_f32 v3, v10, s17, v26
	v_cvt_pk_fp8_f32 v48, v5, v6 op_sel:[0,0,1]
	v_cvt_pk_fp8_f32 v49, v2, v3 op_sel:[0,0,1]
	v_ashrrev_i32_e32 v5, 31, v4
	v_lshlrev_b64 v[2:3], 10, v[4:5]
	v_lshl_add_u64 v[2:3], v[62:63], 0, v[2:3]
	global_store_dwordx2 v[2:3], v[48:49], off nt
	ds_read2_b32 v[2:3], v54 offset1:33
	v_mov_b32_e32 v4, 0
	ds_read2_b32 v[6:7], v54 offset0:66 offset1:99
	ds_read2_b32 v[8:9], v54 offset0:132 offset1:165
	ds_read2_b32 v[10:11], v54 offset0:198 offset1:231
	s_waitcnt lgkmcnt(0)
	v_mul_f32_e32 v2, 0x42800000, v2
	v_mul_f32_e32 v3, 0x42800000, v3
	v_med3_f32 v2, v2, s17, v26
	v_med3_f32 v3, v3, s17, v26
	v_cvt_pk_fp8_f32 v4, v2, v3
	v_mul_f32_e32 v5, 0x42800000, v6
	v_mul_f32_e32 v6, 0x42800000, v7
	v_med3_f32 v3, v5, s17, v26
	v_med3_f32 v5, v6, s17, v26
	v_mul_f32_e32 v2, 0x42800000, v8
	v_cvt_pk_fp8_f32 v4, v3, v5 op_sel:[0,0,1]
	v_mul_f32_e32 v3, 0x42800000, v9
	v_med3_f32 v2, v2, s17, v26
	v_med3_f32 v3, v3, s17, v26
	v_mov_b32_e32 v5, 0
	v_cvt_pk_fp8_f32 v5, v2, v3
	v_mul_f32_e32 v6, 0x42800000, v10
	v_mul_f32_e32 v2, 0x42800000, v11
	v_med3_f32 v3, v6, s17, v26
	v_med3_f32 v2, v2, s17, v26
	v_cvt_pk_fp8_f32 v5, v3, v2 op_sel:[0,0,1]
	v_or_b32_e32 v2, s0, v1
	v_ashrrev_i32_e32 v3, 31, v2
	v_lshlrev_b64 v[2:3], 10, v[2:3]
	v_lshl_add_u64 v[2:3], v[62:63], 0, v[2:3]
	global_store_dwordx2 v[2:3], v[4:5], off nt
	ds_read2_b32 v[2:3], v55 offset1:33
	ds_read2_b32 v[4:5], v55 offset0:66 offset1:99
	s_waitcnt lgkmcnt(0)
	v_mul_f32_e32 v2, 0x42800000, v2
	v_mul_f32_e32 v3, 0x42800000, v3
	v_mul_f32_e32 v6, 0x42800000, v4
	v_med3_f32 v4, v2, s17, v26
	v_med3_f32 v3, v3, s17, v26
	v_mov_b32_e32 v2, 0
	v_mul_f32_e32 v8, 0x42800000, v5
	v_cvt_pk_fp8_f32 v2, v4, v3
	ds_read2_b32 v[4:5], v55 offset0:132 offset1:165
	v_med3_f32 v3, v6, s17, v26
	ds_read2_b32 v[6:7], v55 offset0:198 offset1:231
	v_med3_f32 v8, v8, s17, v26
	v_cvt_pk_fp8_f32 v2, v3, v8 op_sel:[0,0,1]
	s_waitcnt lgkmcnt(0)
	v_mul_f32_e32 v3, 0x42800000, v4
	v_mul_f32_e32 v4, 0x42800000, v5
	v_mul_f32_e32 v5, 0x42800000, v6
	v_med3_f32 v6, v3, s17, v26
	v_med3_f32 v4, v4, s17, v26
	v_mov_b32_e32 v3, 0
	v_cvt_pk_fp8_f32 v3, v6, v4
	v_mul_f32_e32 v4, 0x42800000, v7
	v_med3_f32 v5, v5, s17, v26
	v_med3_f32 v4, v4, s17, v26
	v_cvt_pk_fp8_f32 v3, v5, v4 op_sel:[0,0,1]
	v_or_b32_e32 v4, s0, v50
	v_ashrrev_i32_e32 v5, 31, v4
	v_lshlrev_b64 v[4:5], 10, v[4:5]
	v_lshl_add_u64 v[4:5], v[62:63], 0, v[4:5]
	global_store_dwordx2 v[4:5], v[2:3], off nt
	ds_read2_b32 v[2:3], v56 offset1:33
	ds_read2_b32 v[4:5], v56 offset0:66 offset1:99
	s_waitcnt lgkmcnt(0)
	v_mul_f32_e32 v2, 0x42800000, v2
	v_mul_f32_e32 v3, 0x42800000, v3
	v_mul_f32_e32 v6, 0x42800000, v4
	v_med3_f32 v4, v2, s17, v26
	v_med3_f32 v3, v3, s17, v26
	v_mov_b32_e32 v2, 0
	v_mul_f32_e32 v8, 0x42800000, v5
	v_cvt_pk_fp8_f32 v2, v4, v3
	ds_read2_b32 v[4:5], v56 offset0:132 offset1:165
	v_med3_f32 v3, v6, s17, v26
	ds_read2_b32 v[6:7], v56 offset0:198 offset1:231
	v_med3_f32 v8, v8, s17, v26
	v_cvt_pk_fp8_f32 v2, v3, v8 op_sel:[0,0,1]
	s_waitcnt lgkmcnt(0)
	v_mul_f32_e32 v3, 0x42800000, v4
	v_mul_f32_e32 v4, 0x42800000, v5
	v_mul_f32_e32 v5, 0x42800000, v6
	v_med3_f32 v6, v3, s17, v26
	v_med3_f32 v4, v4, s17, v26
	v_mov_b32_e32 v3, 0
	v_cvt_pk_fp8_f32 v3, v6, v4
	v_mul_f32_e32 v4, 0x42800000, v7
	v_med3_f32 v5, v5, s17, v26
	v_med3_f32 v4, v4, s17, v26
	v_cvt_pk_fp8_f32 v3, v5, v4 op_sel:[0,0,1]
	v_or_b32_e32 v4, s0, v51
	v_ashrrev_i32_e32 v5, 31, v4
	v_lshlrev_b64 v[4:5], 10, v[4:5]
	v_lshl_add_u64 v[4:5], v[62:63], 0, v[4:5]
	global_store_dwordx2 v[4:5], v[2:3], off nt
	s_waitcnt lgkmcnt(0)
	s_branch .LBB0_212

.LBB0_830:
	s_mul_hi_i32 s0, s21, 0x2aaaaaab
	s_lshr_b32 s1, s0, 31
	s_ashr_i32 s0, s0, 8
	s_add_i32 s16, s0, s1
	s_mul_i32 s0, s16, 0xfffffa00
	s_add_i32 s24, s21, s0
	s_lshr_b32 s0, s24, 22
	s_and_b32 s0, s0, 0x1ff
	s_add_i32 s25, s24, s0
	s_and_b32 s0, s25, 0xfe00
	s_sub_i32 s0, s24, s0
	s_sext_i32_i16 s1, s0
	s_bfe_u32 s1, s1, 0x5001a
	s_add_i32 s1, s0, s1
	s_sext_i32_i16 s8, s1
	s_and_b32 s1, s1, 0xffe0
	s_lshl_b32 s23, s8, 1
	s_sub_i32 s0, s0, s1
	s_andn2_b32 s23, s23, 63
	s_sext_i32_i16 s22, s0
	s_lshl_b32 s8, s22, 5
	v_or_b32_e32 v20, s23, v26
	s_mov_b64 s[18:19], -1
	s_cmpk_gt_i32 s24, 0x3ff
	v_ashrrev_i32_e32 v21, 31, v20
	v_or_b32_e32 v18, 8, v20
	v_or_b32_e32 v16, 16, v20
	v_or_b32_e32 v14, 24, v20
	v_or_b32_e32 v12, 32, v20
	v_or_b32_e32 v10, 40, v20
	v_or_b32_e32 v8, 48, v20
	v_or_b32_e32 v6, 56, v20
	s_cbranch_scc0 .LBB0_832
	s_ashr_i32 s17, s16, 31
	s_lshl_b64 s[0:1], s[16:17], 20
	s_lshl_b64 s[18:19], s[16:17], 22
	s_add_u32 s17, s10, s18
	s_addc_u32 s18, s11, s19
	s_add_u32 s19, s6, s0
	s_addc_u32 s26, s7, s1
	s_ashr_i32 s9, s8, 31
	s_lshl_b64 s[0:1], s[8:9], 2
	s_add_u32 s0, s17, s0
	s_addc_u32 s1, s18, s1
	v_lshl_add_u64 v[72:73], s[0:1], 0, v[2:3]
	v_lshlrev_b64 v[22:23], 12, v[20:21]
	v_lshl_add_u64 v[22:23], v[72:73], 0, v[22:23]
	v_ashrrev_i32_e32 v19, 31, v18
	global_load_dwordx4 v[22:25], v[22:23], off nt
	v_lshlrev_b64 v[48:49], 12, v[18:19]
	v_lshl_add_u64 v[48:49], v[72:73], 0, v[48:49]
	v_ashrrev_i32_e32 v17, 31, v16
	global_load_dwordx4 v[48:51], v[48:49], off nt
	v_lshlrev_b64 v[52:53], 12, v[16:17]
	v_lshl_add_u64 v[52:53], v[72:73], 0, v[52:53]
	v_ashrrev_i32_e32 v15, 31, v14
	global_load_dwordx4 v[52:55], v[52:53], off nt
	v_lshlrev_b64 v[56:57], 12, v[14:15]
	v_lshl_add_u64 v[56:57], v[72:73], 0, v[56:57]
	v_ashrrev_i32_e32 v13, 31, v12
	global_load_dwordx4 v[56:59], v[56:57], off nt
	v_lshlrev_b64 v[60:61], 12, v[12:13]
	v_lshl_add_u64 v[60:61], v[72:73], 0, v[60:61]
	v_ashrrev_i32_e32 v11, 31, v10
	global_load_dwordx4 v[60:63], v[60:61], off nt
	v_lshlrev_b64 v[64:65], 12, v[10:11]
	v_lshl_add_u64 v[64:65], v[72:73], 0, v[64:65]
	v_ashrrev_i32_e32 v9, 31, v8
	global_load_dwordx4 v[64:67], v[64:65], off nt
	v_lshlrev_b64 v[68:69], 12, v[8:9]
	v_lshl_add_u64 v[68:69], v[72:73], 0, v[68:69]
	v_ashrrev_i32_e32 v7, 31, v6
	global_load_dwordx4 v[68:71], v[68:69], off nt
	v_lshlrev_b64 v[74:75], 12, v[6:7]
	v_lshl_add_u64 v[72:73], v[72:73], 0, v[74:75]
	global_load_dwordx4 v[72:75], v[72:73], off nt
	s_ashr_i32 s1, s23, 31
	s_add_u32 s0, s19, s23
	s_addc_u32 s1, s26, s1
	s_waitcnt vmcnt(0)
	ds_write2_b32 v31, v22, v23 offset1:1
	ds_write2_b32 v31, v24, v25 offset0:2 offset1:3
	s_waitcnt vmcnt(6)
	ds_write2_b32 v32, v48, v49 offset1:1
	ds_write2_b32 v33, v50, v51 offset1:1
	s_waitcnt vmcnt(5)
	ds_write2_b32 v34, v52, v53 offset1:1
	ds_write2_b32 v35, v54, v55 offset1:1
	s_waitcnt vmcnt(4)
	ds_write2_b32 v36, v56, v57 offset1:1
	ds_write2_b32 v37, v58, v59 offset1:1
	s_waitcnt vmcnt(3)
	ds_write2_b32 v38, v60, v61 offset1:1
	ds_write2_b32 v39, v62, v63 offset1:1
	s_waitcnt vmcnt(2)
	ds_write2_b32 v40, v64, v65 offset1:1
	ds_write2_b32 v41, v66, v67 offset1:1
	s_waitcnt vmcnt(1)
	ds_write2_b32 v42, v68, v69 offset1:1
	ds_write2_b32 v43, v70, v71 offset1:1
	s_waitcnt vmcnt(0)
	ds_write2_b32 v44, v72, v73 offset1:1
	ds_write2_b32 v45, v74, v75 offset1:1
	s_waitcnt lgkmcnt(0)
	ds_read_b32 v7, v30
	ds_read_b32 v9, v30 offset:132
	ds_read_b32 v11, v30 offset:264
	ds_read_b32 v13, v30 offset:396
	v_mov_b32_e32 v24, v3
	s_waitcnt lgkmcnt(0)
	v_mul_f32_e32 v7, 0x43000000, v7
	s_waitcnt lgkmcnt(2)
	v_mul_f32_e32 v9, 0x43000000, v9
	v_med3_f32 v7, v7, s20, v46
	v_med3_f32 v9, v9, s20, v46
	v_cvt_pk_fp8_f32 v24, v7, v9
	s_waitcnt lgkmcnt(1)
	v_mul_f32_e32 v11, 0x43000000, v11
	s_waitcnt lgkmcnt(0)
	v_mul_f32_e32 v13, 0x43000000, v13
	v_med3_f32 v7, v11, s20, v46
	v_med3_f32 v9, v13, s20, v46
	v_cvt_pk_fp8_f32 v24, v7, v9 op_sel:[0,0,1]
	ds_read_b32 v7, v30 offset:528
	ds_read_b32 v9, v30 offset:660
	ds_read_b32 v11, v30 offset:792
	ds_read_b32 v13, v30 offset:924
	v_mov_b32_e32 v25, v3
	s_waitcnt lgkmcnt(3)
	v_mul_f32_e32 v7, 0x43000000, v7
	s_waitcnt lgkmcnt(2)
	v_mul_f32_e32 v9, 0x43000000, v9
	v_med3_f32 v7, v7, s20, v46
	v_med3_f32 v9, v9, s20, v46
	v_cvt_pk_fp8_f32 v25, v7, v9
	s_waitcnt lgkmcnt(1)
	v_mul_f32_e32 v11, 0x43000000, v11
	s_waitcnt lgkmcnt(0)
	v_mul_f32_e32 v13, 0x43000000, v13
	v_med3_f32 v7, v11, s20, v46
	v_med3_f32 v9, v13, s20, v46
	v_cvt_pk_fp8_f32 v25, v7, v9 op_sel:[0,0,1]
	v_or_b32_e32 v48, s8, v26
	v_ashrrev_i32_e32 v49, 31, v48
	v_lshl_add_u64 v[22:23], s[0:1], 0, v[4:5]
	v_lshlrev_b64 v[48:49], 10, v[48:49]
	v_lshl_add_u64 v[48:49], v[22:23], 0, v[48:49]
	global_store_dwordx2 v[48:49], v[24:25], off nt
	ds_read_b32 v7, v30 offset:32
	ds_read_b32 v9, v30 offset:164
	ds_read_b32 v11, v30 offset:296
	ds_read_b32 v13, v30 offset:428
	v_mov_b32_e32 v24, v3
	s_waitcnt lgkmcnt(0)
	v_mul_f32_e32 v7, 0x43000000, v7
	v_mul_f32_e32 v9, 0x43000000, v9
	v_med3_f32 v7, v7, s20, v46
	v_med3_f32 v9, v9, s20, v46
	v_cvt_pk_fp8_f32 v24, v7, v9
	v_mul_f32_e32 v11, 0x43000000, v11
	v_mul_f32_e32 v13, 0x43000000, v13
	v_med3_f32 v7, v11, s20, v46
	v_med3_f32 v9, v13, s20, v46
	v_cvt_pk_fp8_f32 v24, v7, v9 op_sel:[0,0,1]
	ds_read_b32 v7, v30 offset:560
	ds_read_b32 v9, v30 offset:692
	ds_read_b32 v11, v30 offset:824
	ds_read_b32 v13, v30 offset:956
	v_mov_b32_e32 v25, v3
	s_waitcnt lgkmcnt(0)
	v_mul_f32_e32 v7, 0x43000000, v7
	v_mul_f32_e32 v9, 0x43000000, v9
	v_med3_f32 v7, v7, s20, v46
	v_med3_f32 v9, v9, s20, v46
	v_cvt_pk_fp8_f32 v25, v7, v9
	v_mul_f32_e32 v11, 0x43000000, v11
	v_mul_f32_e32 v13, 0x43000000, v13
	v_med3_f32 v7, v11, s20, v46
	v_med3_f32 v9, v13, s20, v46
	v_cvt_pk_fp8_f32 v25, v7, v9 op_sel:[0,0,1]
	v_or_b32_e32 v48, s8, v27
	v_ashrrev_i32_e32 v49, 31, v48
	v_lshlrev_b64 v[48:49], 10, v[48:49]
	v_lshl_add_u64 v[48:49], v[22:23], 0, v[48:49]
	global_store_dwordx2 v[48:49], v[24:25], off nt
	ds_read_b32 v7, v30 offset:64
	ds_read_b32 v9, v30 offset:196
	ds_read_b32 v11, v30 offset:328
	ds_read_b32 v13, v30 offset:460
	v_mov_b32_e32 v24, v3
	s_waitcnt lgkmcnt(0)
	v_mul_f32_e32 v7, 0x43000000, v7
	v_mul_f32_e32 v9, 0x43000000, v9
	v_med3_f32 v7, v7, s20, v46
	v_med3_f32 v9, v9, s20, v46
	v_cvt_pk_fp8_f32 v24, v7, v9
	v_mul_f32_e32 v11, 0x43000000, v11
	v_mul_f32_e32 v13, 0x43000000, v13
	v_med3_f32 v7, v11, s20, v46
	v_med3_f32 v9, v13, s20, v46
	v_cvt_pk_fp8_f32 v24, v7, v9 op_sel:[0,0,1]
	ds_read_b32 v7, v30 offset:592
	ds_read_b32 v9, v30 offset:724
	ds_read_b32 v11, v30 offset:856
	ds_read_b32 v13, v30 offset:988
	v_mov_b32_e32 v25, v3
	s_waitcnt lgkmcnt(0)
	v_mul_f32_e32 v7, 0x43000000, v7
	v_mul_f32_e32 v9, 0x43000000, v9
	v_med3_f32 v7, v7, s20, v46
	v_med3_f32 v9, v9, s20, v46
	v_cvt_pk_fp8_f32 v25, v7, v9
	v_mul_f32_e32 v11, 0x43000000, v11
	v_mul_f32_e32 v13, 0x43000000, v13
	v_med3_f32 v7, v11, s20, v46
	v_med3_f32 v9, v13, s20, v46
	v_cvt_pk_fp8_f32 v25, v7, v9 op_sel:[0,0,1]
	v_or_b32_e32 v48, s8, v28
	v_ashrrev_i32_e32 v49, 31, v48
	v_lshlrev_b64 v[48:49], 10, v[48:49]
	v_lshl_add_u64 v[48:49], v[22:23], 0, v[48:49]
	global_store_dwordx2 v[48:49], v[24:25], off nt
	ds_read_b32 v7, v30 offset:96
	ds_read_b32 v9, v30 offset:228
	ds_read_b32 v11, v30 offset:360
	ds_read_b32 v13, v30 offset:492
	v_mov_b32_e32 v24, v3
	s_waitcnt lgkmcnt(0)
	v_mul_f32_e32 v7, 0x43000000, v7
	v_mul_f32_e32 v9, 0x43000000, v9
	v_med3_f32 v7, v7, s20, v46
	v_med3_f32 v9, v9, s20, v46
	v_cvt_pk_fp8_f32 v24, v7, v9
	v_mul_f32_e32 v11, 0x43000000, v11
	v_mul_f32_e32 v13, 0x43000000, v13
	v_med3_f32 v7, v11, s20, v46
	v_med3_f32 v9, v13, s20, v46
	v_cvt_pk_fp8_f32 v24, v7, v9 op_sel:[0,0,1]
	ds_read_b32 v7, v30 offset:624
	ds_read_b32 v9, v30 offset:756
	ds_read_b32 v11, v30 offset:888
	ds_read_b32 v13, v30 offset:1020
	v_mov_b32_e32 v25, v3
	s_waitcnt lgkmcnt(0)
	v_mul_f32_e32 v7, 0x43000000, v7
	v_mul_f32_e32 v9, 0x43000000, v9
	v_med3_f32 v7, v7, s20, v46
	v_med3_f32 v9, v9, s20, v46
	v_cvt_pk_fp8_f32 v25, v7, v9
	v_mul_f32_e32 v11, 0x43000000, v11
	v_mul_f32_e32 v13, 0x43000000, v13
	v_med3_f32 v7, v11, s20, v46
	v_med3_f32 v9, v13, s20, v46
	v_cvt_pk_fp8_f32 v25, v7, v9 op_sel:[0,0,1]
	v_or_b32_e32 v48, s8, v29
	v_ashrrev_i32_e32 v49, 31, v48
	v_lshlrev_b64 v[48:49], 10, v[48:49]
	v_lshl_add_u64 v[22:23], v[22:23], 0, v[48:49]
	global_store_dwordx2 v[22:23], v[24:25], off nt
	s_waitcnt lgkmcnt(0)
	s_cbranch_execnz .LBB0_829
	s_branch .LBB0_833

.LBB0_833:
	s_sext_i32_i16 s0, s25
	s_lshr_b32 s0, s0, 9
	s_addk_i32 s24, 0x1ff
	s_cmpk_lt_u32 s24, 0x3ff
	s_cselect_b32 s9, s13, s15
	s_cselect_b32 s19, s12, s14
	s_ashr_i32 s17, s16, 31
	s_sext_i32_i16 s18, s0
	s_lshl_b64 s[0:1], s[16:17], 22
	s_add_u32 s19, s19, s0
	s_addc_u32 s24, s9, s1
	s_lshl_b64 s[0:1], s[16:17], 21
	s_add_u32 s16, s4, s0
	s_addc_u32 s17, s5, s1
	s_ashr_i32 s9, s8, 31
	s_lshl_b64 s[0:1], s[8:9], 2
	s_add_u32 s0, s19, s0
	s_addc_u32 s1, s24, s1
	v_lshl_add_u64 v[22:23], s[0:1], 0, v[2:3]
	s_mov_b64 s[0:1], 0x4000000
	v_lshl_add_u64 v[24:25], v[22:23], 0, s[0:1]
	v_lshlrev_b64 v[20:21], 12, v[20:21]
	v_lshl_add_u64 v[20:21], v[24:25], 0, v[20:21]
	v_ashrrev_i32_e32 v19, 31, v18
	global_load_dwordx4 v[20:23], v[20:21], off nt
	v_lshlrev_b64 v[18:19], 12, v[18:19]
	v_lshl_add_u64 v[18:19], v[24:25], 0, v[18:19]
	v_ashrrev_i32_e32 v17, 31, v16
	global_load_dwordx4 v[48:51], v[18:19], off nt
	v_lshlrev_b64 v[16:17], 12, v[16:17]
	v_lshl_add_u64 v[16:17], v[24:25], 0, v[16:17]
	v_ashrrev_i32_e32 v15, 31, v14
	global_load_dwordx4 v[16:19], v[16:17], off nt
	v_lshlrev_b64 v[14:15], 12, v[14:15]
	v_lshl_add_u64 v[14:15], v[24:25], 0, v[14:15]
	v_ashrrev_i32_e32 v13, 31, v12
	global_load_dwordx4 v[52:55], v[14:15], off nt
	v_lshlrev_b64 v[12:13], 12, v[12:13]
	v_lshl_add_u64 v[12:13], v[24:25], 0, v[12:13]
	v_ashrrev_i32_e32 v11, 31, v10
	global_load_dwordx4 v[12:15], v[12:13], off nt
	v_lshlrev_b64 v[10:11], 12, v[10:11]
	v_lshl_add_u64 v[10:11], v[24:25], 0, v[10:11]
	v_ashrrev_i32_e32 v9, 31, v8
	global_load_dwordx4 v[56:59], v[10:11], off nt
	v_lshlrev_b64 v[8:9], 12, v[8:9]
	v_lshl_add_u64 v[8:9], v[24:25], 0, v[8:9]
	v_ashrrev_i32_e32 v7, 31, v6
	global_load_dwordx4 v[8:11], v[8:9], off nt
	v_lshlrev_b64 v[6:7], 12, v[6:7]
	v_lshl_add_u64 v[6:7], v[24:25], 0, v[6:7]
	global_load_dwordx4 v[60:63], v[6:7], off nt
	s_lshl_b32 s1, s18, 7
	s_ashr_i32 s0, s23, 31
	s_add_u32 s16, s16, s23
	s_addc_u32 s17, s17, s0
	s_lshl_b32 s0, s22, 6
	s_and_b32 s0, s0, 0xffffff00
	s_add_i32 s0, s0, s1
	s_and_b32 s1, s8, 0x60
	s_or_b32 s8, s0, s1
	v_lshl_add_u64 v[6:7], s[16:17], 0, v[4:5]
	s_waitcnt vmcnt(0)
	ds_write2_b32 v31, v20, v21 offset1:1
	ds_write2_b32 v31, v22, v23 offset0:2 offset1:3
	ds_write2_b32 v32, v48, v49 offset1:1
	ds_write2_b32 v33, v50, v51 offset1:1
	ds_write2_b32 v34, v16, v17 offset1:1
	ds_write2_b32 v35, v18, v19 offset1:1
	ds_write2_b32 v36, v52, v53 offset1:1
	ds_write2_b32 v37, v54, v55 offset1:1
	ds_write2_b32 v38, v12, v13 offset1:1
	ds_write2_b32 v39, v14, v15 offset1:1
	ds_write2_b32 v40, v56, v57 offset1:1
	ds_write2_b32 v41, v58, v59 offset1:1
	ds_write2_b32 v42, v8, v9 offset1:1
	ds_write2_b32 v43, v10, v11 offset1:1
	ds_write2_b32 v44, v60, v61 offset1:1
	ds_write2_b32 v45, v62, v63 offset1:1
	s_waitcnt lgkmcnt(0)
	ds_read_b32 v8, v30
	ds_read_b32 v9, v30 offset:132
	ds_read_b32 v10, v30 offset:264
	ds_read_b32 v11, v30 offset:396
	s_waitcnt lgkmcnt(0)
	v_mul_f32_e32 v8, 0x42800000, v8
	v_mul_f32_e32 v9, 0x42800000, v9
	v_med3_f32 v12, v8, s20, v46
	v_med3_f32 v9, v9, s20, v46
	v_mov_b32_e32 v8, v3
	v_cvt_pk_fp8_f32 v8, v12, v9
	v_mul_f32_e32 v10, 0x42800000, v10
	v_mul_f32_e32 v11, 0x42800000, v11
	v_med3_f32 v9, v10, s20, v46
	v_med3_f32 v10, v11, s20, v46
	v_cvt_pk_fp8_f32 v8, v9, v10 op_sel:[0,0,1]
	ds_read_b32 v9, v30 offset:528
	ds_read_b32 v10, v30 offset:660
	ds_read_b32 v11, v30 offset:792
	ds_read_b32 v12, v30 offset:924
	s_waitcnt lgkmcnt(3)
	v_mul_f32_e32 v9, 0x42800000, v9
	s_waitcnt lgkmcnt(2)
	v_mul_f32_e32 v10, 0x42800000, v10
	v_med3_f32 v13, v9, s20, v46
	v_med3_f32 v10, v10, s20, v46
	v_mov_b32_e32 v9, v3
	v_cvt_pk_fp8_f32 v9, v13, v10
	s_waitcnt lgkmcnt(1)
	v_mul_f32_e32 v11, 0x42800000, v11
	s_waitcnt lgkmcnt(0)
	v_mul_f32_e32 v12, 0x42800000, v12
	v_med3_f32 v10, v11, s20, v46
	v_med3_f32 v11, v12, s20, v46
	v_cvt_pk_fp8_f32 v9, v10, v11 op_sel:[0,0,1]
	v_or_b32_e32 v10, s8, v26
	v_ashrrev_i32_e32 v11, 31, v10
	v_lshlrev_b64 v[10:11], 10, v[10:11]
	v_lshl_add_u64 v[10:11], v[6:7], 0, v[10:11]
	global_store_dwordx2 v[10:11], v[8:9], off nt
	ds_read_b32 v8, v30 offset:32
	ds_read_b32 v9, v30 offset:164
	ds_read_b32 v10, v30 offset:296
	ds_read_b32 v11, v30 offset:428
	s_waitcnt lgkmcnt(0)
	v_mul_f32_e32 v8, 0x42800000, v8
	v_mul_f32_e32 v9, 0x42800000, v9
	v_med3_f32 v12, v8, s20, v46
	v_med3_f32 v9, v9, s20, v46
	v_mov_b32_e32 v8, v3
	v_cvt_pk_fp8_f32 v8, v12, v9
	v_mul_f32_e32 v10, 0x42800000, v10
	v_mul_f32_e32 v11, 0x42800000, v11
	v_med3_f32 v9, v10, s20, v46
	v_med3_f32 v10, v11, s20, v46
	v_cvt_pk_fp8_f32 v8, v9, v10 op_sel:[0,0,1]
	ds_read_b32 v9, v30 offset:560
	ds_read_b32 v10, v30 offset:692
	ds_read_b32 v11, v30 offset:824
	ds_read_b32 v12, v30 offset:956
	s_waitcnt lgkmcnt(0)
	v_mul_f32_e32 v9, 0x42800000, v9
	v_mul_f32_e32 v10, 0x42800000, v10
	v_med3_f32 v13, v9, s20, v46
	v_med3_f32 v10, v10, s20, v46
	v_mov_b32_e32 v9, v3
	v_cvt_pk_fp8_f32 v9, v13, v10
	v_mul_f32_e32 v11, 0x42800000, v11
	v_mul_f32_e32 v12, 0x42800000, v12
	v_med3_f32 v10, v11, s20, v46
	v_med3_f32 v11, v12, s20, v46
	v_cvt_pk_fp8_f32 v9, v10, v11 op_sel:[0,0,1]
	v_or_b32_e32 v10, s8, v27
	v_ashrrev_i32_e32 v11, 31, v10
	v_lshlrev_b64 v[10:11], 10, v[10:11]
	v_lshl_add_u64 v[10:11], v[6:7], 0, v[10:11]
	global_store_dwordx2 v[10:11], v[8:9], off nt
	ds_read_b32 v8, v30 offset:64
	ds_read_b32 v9, v30 offset:196
	ds_read_b32 v10, v30 offset:328
	ds_read_b32 v11, v30 offset:460
	s_waitcnt lgkmcnt(0)
	v_mul_f32_e32 v8, 0x42800000, v8
	v_mul_f32_e32 v9, 0x42800000, v9
	v_med3_f32 v12, v8, s20, v46
	v_med3_f32 v9, v9, s20, v46
	v_mov_b32_e32 v8, v3
	v_cvt_pk_fp8_f32 v8, v12, v9
	v_mul_f32_e32 v10, 0x42800000, v10
	v_mul_f32_e32 v11, 0x42800000, v11
	v_med3_f32 v9, v10, s20, v46
	v_med3_f32 v10, v11, s20, v46
	v_cvt_pk_fp8_f32 v8, v9, v10 op_sel:[0,0,1]
	ds_read_b32 v9, v30 offset:592
	ds_read_b32 v10, v30 offset:724
	ds_read_b32 v11, v30 offset:856
	ds_read_b32 v12, v30 offset:988
	s_waitcnt lgkmcnt(0)
	v_mul_f32_e32 v9, 0x42800000, v9
	v_mul_f32_e32 v10, 0x42800000, v10
	v_med3_f32 v13, v9, s20, v46
	v_med3_f32 v10, v10, s20, v46
	v_mov_b32_e32 v9, v3
	v_cvt_pk_fp8_f32 v9, v13, v10
	v_mul_f32_e32 v11, 0x42800000, v11
	v_mul_f32_e32 v12, 0x42800000, v12
	v_med3_f32 v10, v11, s20, v46
	v_med3_f32 v11, v12, s20, v46
	v_cvt_pk_fp8_f32 v9, v10, v11 op_sel:[0,0,1]
	v_or_b32_e32 v10, s8, v28
	v_ashrrev_i32_e32 v11, 31, v10
	v_lshlrev_b64 v[10:11], 10, v[10:11]
	v_lshl_add_u64 v[10:11], v[6:7], 0, v[10:11]
	global_store_dwordx2 v[10:11], v[8:9], off nt
	ds_read_b32 v8, v30 offset:96
	ds_read_b32 v9, v30 offset:228
	ds_read_b32 v10, v30 offset:360
	ds_read_b32 v11, v30 offset:492
	s_waitcnt lgkmcnt(0)
	v_mul_f32_e32 v8, 0x42800000, v8
	v_mul_f32_e32 v9, 0x42800000, v9
	v_med3_f32 v12, v8, s20, v46
	v_med3_f32 v9, v9, s20, v46
	v_mov_b32_e32 v8, v3
	v_cvt_pk_fp8_f32 v8, v12, v9
	v_mul_f32_e32 v10, 0x42800000, v10
	v_mul_f32_e32 v11, 0x42800000, v11
	v_med3_f32 v9, v10, s20, v46
	v_med3_f32 v10, v11, s20, v46
	v_cvt_pk_fp8_f32 v8, v9, v10 op_sel:[0,0,1]
	ds_read_b32 v9, v30 offset:624
	ds_read_b32 v10, v30 offset:756
	ds_read_b32 v11, v30 offset:888
	ds_read_b32 v12, v30 offset:1020
	s_waitcnt lgkmcnt(0)
	v_mul_f32_e32 v9, 0x42800000, v9
	v_mul_f32_e32 v10, 0x42800000, v10
	v_med3_f32 v13, v9, s20, v46
	v_med3_f32 v10, v10, s20, v46
	v_mov_b32_e32 v9, v3
	v_cvt_pk_fp8_f32 v9, v13, v10
	v_mul_f32_e32 v11, 0x42800000, v11
	v_mul_f32_e32 v12, 0x42800000, v12
	v_med3_f32 v10, v11, s20, v46
	v_med3_f32 v11, v12, s20, v46
	v_cvt_pk_fp8_f32 v9, v10, v11 op_sel:[0,0,1]
	v_or_b32_e32 v10, s8, v29
	v_ashrrev_i32_e32 v11, 31, v10
	v_lshlrev_b64 v[10:11], 10, v[10:11]
	v_lshl_add_u64 v[6:7], v[6:7], 0, v[10:11]
	global_store_dwordx2 v[6:7], v[8:9], off nt
	s_waitcnt lgkmcnt(0)
	s_branch .LBB0_829

.LBB0_1444:
	s_mul_hi_i32 s0, s11, 0x2aaaaaab
	s_lshr_b32 s1, s0, 31
	s_ashr_i32 s0, s0, 8
	s_add_i32 s14, s0, s1
	s_mul_i32 s0, s14, 0xfffffa00
	s_add_i32 s24, s11, s0
	s_lshr_b32 s0, s24, 22
	s_and_b32 s0, s0, 0x1ff
	s_add_i32 s25, s24, s0
	s_and_b32 s0, s25, 0xfe00
	s_sub_i32 s0, s24, s0
	s_sext_i32_i16 s1, s0
	s_bfe_u32 s1, s1, 0x5001a
	s_add_i32 s1, s0, s1
	s_sext_i32_i16 s12, s1
	s_and_b32 s1, s1, 0xffe0
	s_lshl_b32 s23, s12, 1
	s_sub_i32 s0, s0, s1
	s_andn2_b32 s23, s23, 63
	s_sext_i32_i16 s22, s0
	s_lshl_b32 s12, s22, 5
	v_or_b32_e32 v20, s23, v26
	s_mov_b64 s[20:21], -1
	s_cmpk_gt_i32 s24, 0x3ff
	v_ashrrev_i32_e32 v21, 31, v20
	v_or_b32_e32 v18, 8, v20
	v_or_b32_e32 v16, 16, v20
	v_or_b32_e32 v14, 24, v20
	v_or_b32_e32 v12, 32, v20
	v_or_b32_e32 v10, 40, v20
	v_or_b32_e32 v8, 48, v20
	v_or_b32_e32 v6, 56, v20
	s_cbranch_scc0 .LBB0_1446
	s_ashr_i32 s15, s14, 31
	s_lshl_b64 s[0:1], s[14:15], 20
	s_lshl_b64 s[20:21], s[14:15], 22
	s_add_u32 s15, s8, s20
	s_addc_u32 s20, s9, s21
	s_add_u32 s21, s6, s0
	s_addc_u32 s26, s7, s1
	s_ashr_i32 s13, s12, 31
	s_lshl_b64 s[0:1], s[12:13], 2
	s_add_u32 s0, s15, s0
	s_addc_u32 s1, s20, s1
	v_lshl_add_u64 v[72:73], s[0:1], 0, v[2:3]
	v_lshlrev_b64 v[22:23], 12, v[20:21]
	v_lshl_add_u64 v[22:23], v[72:73], 0, v[22:23]
	v_ashrrev_i32_e32 v19, 31, v18
	global_load_dwordx4 v[22:25], v[22:23], off nt
	v_lshlrev_b64 v[48:49], 12, v[18:19]
	v_lshl_add_u64 v[48:49], v[72:73], 0, v[48:49]
	v_ashrrev_i32_e32 v17, 31, v16
	global_load_dwordx4 v[48:51], v[48:49], off nt
	v_lshlrev_b64 v[52:53], 12, v[16:17]
	v_lshl_add_u64 v[52:53], v[72:73], 0, v[52:53]
	v_ashrrev_i32_e32 v15, 31, v14
	global_load_dwordx4 v[52:55], v[52:53], off nt
	v_lshlrev_b64 v[56:57], 12, v[14:15]
	v_lshl_add_u64 v[56:57], v[72:73], 0, v[56:57]
	v_ashrrev_i32_e32 v13, 31, v12
	global_load_dwordx4 v[56:59], v[56:57], off nt
	v_lshlrev_b64 v[60:61], 12, v[12:13]
	v_lshl_add_u64 v[60:61], v[72:73], 0, v[60:61]
	v_ashrrev_i32_e32 v11, 31, v10
	global_load_dwordx4 v[60:63], v[60:61], off nt
	v_lshlrev_b64 v[64:65], 12, v[10:11]
	v_lshl_add_u64 v[64:65], v[72:73], 0, v[64:65]
	v_ashrrev_i32_e32 v9, 31, v8
	global_load_dwordx4 v[64:67], v[64:65], off nt
	v_lshlrev_b64 v[68:69], 12, v[8:9]
	v_lshl_add_u64 v[68:69], v[72:73], 0, v[68:69]
	v_ashrrev_i32_e32 v7, 31, v6
	global_load_dwordx4 v[68:71], v[68:69], off nt
	v_lshlrev_b64 v[74:75], 12, v[6:7]
	v_lshl_add_u64 v[72:73], v[72:73], 0, v[74:75]
	global_load_dwordx4 v[72:75], v[72:73], off nt
	s_ashr_i32 s1, s23, 31
	s_add_u32 s0, s21, s23
	s_addc_u32 s1, s26, s1
	s_waitcnt vmcnt(0)
	ds_write2_b32 v31, v22, v23 offset1:1
	ds_write2_b32 v31, v24, v25 offset0:2 offset1:3
	s_waitcnt vmcnt(6)
	ds_write2_b32 v32, v48, v49 offset1:1
	ds_write2_b32 v33, v50, v51 offset1:1
	s_waitcnt vmcnt(5)
	ds_write2_b32 v34, v52, v53 offset1:1
	ds_write2_b32 v35, v54, v55 offset1:1
	s_waitcnt vmcnt(4)
	ds_write2_b32 v36, v56, v57 offset1:1
	ds_write2_b32 v37, v58, v59 offset1:1
	s_waitcnt vmcnt(3)
	ds_write2_b32 v38, v60, v61 offset1:1
	ds_write2_b32 v39, v62, v63 offset1:1
	s_waitcnt vmcnt(2)
	ds_write2_b32 v40, v64, v65 offset1:1
	ds_write2_b32 v41, v66, v67 offset1:1
	s_waitcnt vmcnt(1)
	ds_write2_b32 v42, v68, v69 offset1:1
	ds_write2_b32 v43, v70, v71 offset1:1
	s_waitcnt vmcnt(0)
	ds_write2_b32 v44, v72, v73 offset1:1
	ds_write2_b32 v45, v74, v75 offset1:1
	s_waitcnt lgkmcnt(0)
	ds_read_b32 v7, v30
	ds_read_b32 v9, v30 offset:132
	ds_read_b32 v11, v30 offset:264
	ds_read_b32 v13, v30 offset:396
	v_mov_b32_e32 v24, v3
	s_waitcnt lgkmcnt(0)
	v_mul_f32_e32 v7, 0x43000000, v7
	s_waitcnt lgkmcnt(2)
	v_mul_f32_e32 v9, 0x43000000, v9
	v_med3_f32 v7, v7, s10, v46
	v_med3_f32 v9, v9, s10, v46
	v_cvt_pk_fp8_f32 v24, v7, v9
	s_waitcnt lgkmcnt(1)
	v_mul_f32_e32 v11, 0x43000000, v11
	s_waitcnt lgkmcnt(0)
	v_mul_f32_e32 v13, 0x43000000, v13
	v_med3_f32 v7, v11, s10, v46
	v_med3_f32 v9, v13, s10, v46
	v_cvt_pk_fp8_f32 v24, v7, v9 op_sel:[0,0,1]
	ds_read_b32 v7, v30 offset:528
	ds_read_b32 v9, v30 offset:660
	ds_read_b32 v11, v30 offset:792
	ds_read_b32 v13, v30 offset:924
	v_mov_b32_e32 v25, v3
	s_waitcnt lgkmcnt(3)
	v_mul_f32_e32 v7, 0x43000000, v7
	s_waitcnt lgkmcnt(2)
	v_mul_f32_e32 v9, 0x43000000, v9
	v_med3_f32 v7, v7, s10, v46
	v_med3_f32 v9, v9, s10, v46
	v_cvt_pk_fp8_f32 v25, v7, v9
	s_waitcnt lgkmcnt(1)
	v_mul_f32_e32 v11, 0x43000000, v11
	s_waitcnt lgkmcnt(0)
	v_mul_f32_e32 v13, 0x43000000, v13
	v_med3_f32 v7, v11, s10, v46
	v_med3_f32 v9, v13, s10, v46
	v_cvt_pk_fp8_f32 v25, v7, v9 op_sel:[0,0,1]
	v_or_b32_e32 v48, s12, v26
	v_ashrrev_i32_e32 v49, 31, v48
	v_lshl_add_u64 v[22:23], s[0:1], 0, v[4:5]
	v_lshlrev_b64 v[48:49], 10, v[48:49]
	v_lshl_add_u64 v[48:49], v[22:23], 0, v[48:49]
	global_store_dwordx2 v[48:49], v[24:25], off nt
	ds_read_b32 v7, v30 offset:32
	ds_read_b32 v9, v30 offset:164
	ds_read_b32 v11, v30 offset:296
	ds_read_b32 v13, v30 offset:428
	v_mov_b32_e32 v24, v3
	s_waitcnt lgkmcnt(0)
	v_mul_f32_e32 v7, 0x43000000, v7
	v_mul_f32_e32 v9, 0x43000000, v9
	v_med3_f32 v7, v7, s10, v46
	v_med3_f32 v9, v9, s10, v46
	v_cvt_pk_fp8_f32 v24, v7, v9
	v_mul_f32_e32 v11, 0x43000000, v11
	v_mul_f32_e32 v13, 0x43000000, v13
	v_med3_f32 v7, v11, s10, v46
	v_med3_f32 v9, v13, s10, v46
	v_cvt_pk_fp8_f32 v24, v7, v9 op_sel:[0,0,1]
	ds_read_b32 v7, v30 offset:560
	ds_read_b32 v9, v30 offset:692
	ds_read_b32 v11, v30 offset:824
	ds_read_b32 v13, v30 offset:956
	v_mov_b32_e32 v25, v3
	s_waitcnt lgkmcnt(0)
	v_mul_f32_e32 v7, 0x43000000, v7
	v_mul_f32_e32 v9, 0x43000000, v9
	v_med3_f32 v7, v7, s10, v46
	v_med3_f32 v9, v9, s10, v46
	v_cvt_pk_fp8_f32 v25, v7, v9
	v_mul_f32_e32 v11, 0x43000000, v11
	v_mul_f32_e32 v13, 0x43000000, v13
	v_med3_f32 v7, v11, s10, v46
	v_med3_f32 v9, v13, s10, v46
	v_cvt_pk_fp8_f32 v25, v7, v9 op_sel:[0,0,1]
	v_or_b32_e32 v48, s12, v27
	v_ashrrev_i32_e32 v49, 31, v48
	v_lshlrev_b64 v[48:49], 10, v[48:49]
	v_lshl_add_u64 v[48:49], v[22:23], 0, v[48:49]
	global_store_dwordx2 v[48:49], v[24:25], off nt
	ds_read_b32 v7, v30 offset:64
	ds_read_b32 v9, v30 offset:196
	ds_read_b32 v11, v30 offset:328
	ds_read_b32 v13, v30 offset:460
	v_mov_b32_e32 v24, v3
	s_waitcnt lgkmcnt(0)
	v_mul_f32_e32 v7, 0x43000000, v7
	v_mul_f32_e32 v9, 0x43000000, v9
	v_med3_f32 v7, v7, s10, v46
	v_med3_f32 v9, v9, s10, v46
	v_cvt_pk_fp8_f32 v24, v7, v9
	v_mul_f32_e32 v11, 0x43000000, v11
	v_mul_f32_e32 v13, 0x43000000, v13
	v_med3_f32 v7, v11, s10, v46
	v_med3_f32 v9, v13, s10, v46
	v_cvt_pk_fp8_f32 v24, v7, v9 op_sel:[0,0,1]
	ds_read_b32 v7, v30 offset:592
	ds_read_b32 v9, v30 offset:724
	ds_read_b32 v11, v30 offset:856
	ds_read_b32 v13, v30 offset:988
	v_mov_b32_e32 v25, v3
	s_waitcnt lgkmcnt(0)
	v_mul_f32_e32 v7, 0x43000000, v7
	v_mul_f32_e32 v9, 0x43000000, v9
	v_med3_f32 v7, v7, s10, v46
	v_med3_f32 v9, v9, s10, v46
	v_cvt_pk_fp8_f32 v25, v7, v9
	v_mul_f32_e32 v11, 0x43000000, v11
	v_mul_f32_e32 v13, 0x43000000, v13
	v_med3_f32 v7, v11, s10, v46
	v_med3_f32 v9, v13, s10, v46
	v_cvt_pk_fp8_f32 v25, v7, v9 op_sel:[0,0,1]
	v_or_b32_e32 v48, s12, v28
	v_ashrrev_i32_e32 v49, 31, v48
	v_lshlrev_b64 v[48:49], 10, v[48:49]
	v_lshl_add_u64 v[48:49], v[22:23], 0, v[48:49]
	global_store_dwordx2 v[48:49], v[24:25], off nt
	ds_read_b32 v7, v30 offset:96
	ds_read_b32 v9, v30 offset:228
	ds_read_b32 v11, v30 offset:360
	ds_read_b32 v13, v30 offset:492
	v_mov_b32_e32 v24, v3
	s_waitcnt lgkmcnt(0)
	v_mul_f32_e32 v7, 0x43000000, v7
	v_mul_f32_e32 v9, 0x43000000, v9
	v_med3_f32 v7, v7, s10, v46
	v_med3_f32 v9, v9, s10, v46
	v_cvt_pk_fp8_f32 v24, v7, v9
	v_mul_f32_e32 v11, 0x43000000, v11
	v_mul_f32_e32 v13, 0x43000000, v13
	v_med3_f32 v7, v11, s10, v46
	v_med3_f32 v9, v13, s10, v46
	v_cvt_pk_fp8_f32 v24, v7, v9 op_sel:[0,0,1]
	ds_read_b32 v7, v30 offset:624
	ds_read_b32 v9, v30 offset:756
	ds_read_b32 v11, v30 offset:888
	ds_read_b32 v13, v30 offset:1020
	v_mov_b32_e32 v25, v3
	s_waitcnt lgkmcnt(0)
	v_mul_f32_e32 v7, 0x43000000, v7
	v_mul_f32_e32 v9, 0x43000000, v9
	v_med3_f32 v7, v7, s10, v46
	v_med3_f32 v9, v9, s10, v46
	v_cvt_pk_fp8_f32 v25, v7, v9
	v_mul_f32_e32 v11, 0x43000000, v11
	v_mul_f32_e32 v13, 0x43000000, v13
	v_med3_f32 v7, v11, s10, v46
	v_med3_f32 v9, v13, s10, v46
	v_cvt_pk_fp8_f32 v25, v7, v9 op_sel:[0,0,1]
	v_or_b32_e32 v48, s12, v29
	v_ashrrev_i32_e32 v49, 31, v48
	v_lshlrev_b64 v[48:49], 10, v[48:49]
	v_lshl_add_u64 v[22:23], v[22:23], 0, v[48:49]
	global_store_dwordx2 v[22:23], v[24:25], off nt
	s_waitcnt lgkmcnt(0)
	s_cbranch_execnz .LBB0_1443
	s_branch .LBB0_1447

.LBB0_1447:
	s_sext_i32_i16 s0, s25
	s_lshr_b32 s0, s0, 9
	s_addk_i32 s24, 0x1ff
	s_cmpk_lt_u32 s24, 0x3ff
	s_cselect_b32 s13, s17, s19
	s_cselect_b32 s21, s16, s18
	s_ashr_i32 s15, s14, 31
	s_sext_i32_i16 s20, s0
	s_lshl_b64 s[0:1], s[14:15], 22
	s_add_u32 s21, s21, s0
	s_addc_u32 s24, s13, s1
	s_lshl_b64 s[0:1], s[14:15], 21
	s_add_u32 s14, s4, s0
	s_addc_u32 s15, s5, s1
	s_ashr_i32 s13, s12, 31
	s_lshl_b64 s[0:1], s[12:13], 2
	s_add_u32 s0, s21, s0
	s_addc_u32 s1, s24, s1
	v_lshl_add_u64 v[22:23], s[0:1], 0, v[2:3]
	s_mov_b64 s[0:1], 0x8000000
	v_lshl_add_u64 v[24:25], v[22:23], 0, s[0:1]
	v_lshlrev_b64 v[20:21], 12, v[20:21]
	v_lshl_add_u64 v[20:21], v[24:25], 0, v[20:21]
	v_ashrrev_i32_e32 v19, 31, v18
	global_load_dwordx4 v[20:23], v[20:21], off nt
	v_lshlrev_b64 v[18:19], 12, v[18:19]
	v_lshl_add_u64 v[18:19], v[24:25], 0, v[18:19]
	v_ashrrev_i32_e32 v17, 31, v16
	global_load_dwordx4 v[48:51], v[18:19], off nt
	v_lshlrev_b64 v[16:17], 12, v[16:17]
	v_lshl_add_u64 v[16:17], v[24:25], 0, v[16:17]
	v_ashrrev_i32_e32 v15, 31, v14
	global_load_dwordx4 v[16:19], v[16:17], off nt
	v_lshlrev_b64 v[14:15], 12, v[14:15]
	v_lshl_add_u64 v[14:15], v[24:25], 0, v[14:15]
	v_ashrrev_i32_e32 v13, 31, v12
	global_load_dwordx4 v[52:55], v[14:15], off nt
	v_lshlrev_b64 v[12:13], 12, v[12:13]
	v_lshl_add_u64 v[12:13], v[24:25], 0, v[12:13]
	v_ashrrev_i32_e32 v11, 31, v10
	global_load_dwordx4 v[12:15], v[12:13], off nt
	v_lshlrev_b64 v[10:11], 12, v[10:11]
	v_lshl_add_u64 v[10:11], v[24:25], 0, v[10:11]
	v_ashrrev_i32_e32 v9, 31, v8
	global_load_dwordx4 v[56:59], v[10:11], off nt
	v_lshlrev_b64 v[8:9], 12, v[8:9]
	v_lshl_add_u64 v[8:9], v[24:25], 0, v[8:9]
	v_ashrrev_i32_e32 v7, 31, v6
	global_load_dwordx4 v[8:11], v[8:9], off nt
	v_lshlrev_b64 v[6:7], 12, v[6:7]
	v_lshl_add_u64 v[6:7], v[24:25], 0, v[6:7]
	global_load_dwordx4 v[60:63], v[6:7], off nt
	s_lshl_b32 s1, s20, 7
	s_ashr_i32 s0, s23, 31
	s_add_u32 s14, s14, s23
	s_addc_u32 s15, s15, s0
	s_lshl_b32 s0, s22, 6
	s_and_b32 s0, s0, 0xffffff00
	s_add_i32 s0, s0, s1
	s_and_b32 s1, s12, 0x60
	s_or_b32 s12, s0, s1
	v_lshl_add_u64 v[6:7], s[14:15], 0, v[4:5]
	s_waitcnt vmcnt(0)
	ds_write2_b32 v31, v20, v21 offset1:1
	ds_write2_b32 v31, v22, v23 offset0:2 offset1:3
	ds_write2_b32 v32, v48, v49 offset1:1
	ds_write2_b32 v33, v50, v51 offset1:1
	ds_write2_b32 v34, v16, v17 offset1:1
	ds_write2_b32 v35, v18, v19 offset1:1
	ds_write2_b32 v36, v52, v53 offset1:1
	ds_write2_b32 v37, v54, v55 offset1:1
	ds_write2_b32 v38, v12, v13 offset1:1
	ds_write2_b32 v39, v14, v15 offset1:1
	ds_write2_b32 v40, v56, v57 offset1:1
	ds_write2_b32 v41, v58, v59 offset1:1
	ds_write2_b32 v42, v8, v9 offset1:1
	ds_write2_b32 v43, v10, v11 offset1:1
	ds_write2_b32 v44, v60, v61 offset1:1
	ds_write2_b32 v45, v62, v63 offset1:1
	s_waitcnt lgkmcnt(0)
	ds_read_b32 v8, v30
	ds_read_b32 v9, v30 offset:132
	ds_read_b32 v10, v30 offset:264
	ds_read_b32 v11, v30 offset:396
	s_waitcnt lgkmcnt(0)
	v_mul_f32_e32 v8, 0x42800000, v8
	v_mul_f32_e32 v9, 0x42800000, v9
	v_med3_f32 v12, v8, s10, v46
	v_med3_f32 v9, v9, s10, v46
	v_mov_b32_e32 v8, v3
	v_cvt_pk_fp8_f32 v8, v12, v9
	v_mul_f32_e32 v10, 0x42800000, v10
	v_mul_f32_e32 v11, 0x42800000, v11
	v_med3_f32 v9, v10, s10, v46
	v_med3_f32 v10, v11, s10, v46
	v_cvt_pk_fp8_f32 v8, v9, v10 op_sel:[0,0,1]
	ds_read_b32 v9, v30 offset:528
	ds_read_b32 v10, v30 offset:660
	ds_read_b32 v11, v30 offset:792
	ds_read_b32 v12, v30 offset:924
	s_waitcnt lgkmcnt(3)
	v_mul_f32_e32 v9, 0x42800000, v9
	s_waitcnt lgkmcnt(2)
	v_mul_f32_e32 v10, 0x42800000, v10
	v_med3_f32 v13, v9, s10, v46
	v_med3_f32 v10, v10, s10, v46
	v_mov_b32_e32 v9, v3
	v_cvt_pk_fp8_f32 v9, v13, v10
	s_waitcnt lgkmcnt(1)
	v_mul_f32_e32 v11, 0x42800000, v11
	s_waitcnt lgkmcnt(0)
	v_mul_f32_e32 v12, 0x42800000, v12
	v_med3_f32 v10, v11, s10, v46
	v_med3_f32 v11, v12, s10, v46
	v_cvt_pk_fp8_f32 v9, v10, v11 op_sel:[0,0,1]
	v_or_b32_e32 v10, s12, v26
	v_ashrrev_i32_e32 v11, 31, v10
	v_lshlrev_b64 v[10:11], 10, v[10:11]
	v_lshl_add_u64 v[10:11], v[6:7], 0, v[10:11]
	global_store_dwordx2 v[10:11], v[8:9], off nt
	ds_read_b32 v8, v30 offset:32
	ds_read_b32 v9, v30 offset:164
	ds_read_b32 v10, v30 offset:296
	ds_read_b32 v11, v30 offset:428
	s_waitcnt lgkmcnt(0)
	v_mul_f32_e32 v8, 0x42800000, v8
	v_mul_f32_e32 v9, 0x42800000, v9
	v_med3_f32 v12, v8, s10, v46
	v_med3_f32 v9, v9, s10, v46
	v_mov_b32_e32 v8, v3
	v_cvt_pk_fp8_f32 v8, v12, v9
	v_mul_f32_e32 v10, 0x42800000, v10
	v_mul_f32_e32 v11, 0x42800000, v11
	v_med3_f32 v9, v10, s10, v46
	v_med3_f32 v10, v11, s10, v46
	v_cvt_pk_fp8_f32 v8, v9, v10 op_sel:[0,0,1]
	ds_read_b32 v9, v30 offset:560
	ds_read_b32 v10, v30 offset:692
	ds_read_b32 v11, v30 offset:824
	ds_read_b32 v12, v30 offset:956
	s_waitcnt lgkmcnt(0)
	v_mul_f32_e32 v9, 0x42800000, v9
	v_mul_f32_e32 v10, 0x42800000, v10
	v_med3_f32 v13, v9, s10, v46
	v_med3_f32 v10, v10, s10, v46
	v_mov_b32_e32 v9, v3
	v_cvt_pk_fp8_f32 v9, v13, v10
	v_mul_f32_e32 v11, 0x42800000, v11
	v_mul_f32_e32 v12, 0x42800000, v12
	v_med3_f32 v10, v11, s10, v46
	v_med3_f32 v11, v12, s10, v46
	v_cvt_pk_fp8_f32 v9, v10, v11 op_sel:[0,0,1]
	v_or_b32_e32 v10, s12, v27
	v_ashrrev_i32_e32 v11, 31, v10
	v_lshlrev_b64 v[10:11], 10, v[10:11]
	v_lshl_add_u64 v[10:11], v[6:7], 0, v[10:11]
	global_store_dwordx2 v[10:11], v[8:9], off nt
	ds_read_b32 v8, v30 offset:64
	ds_read_b32 v9, v30 offset:196
	ds_read_b32 v10, v30 offset:328
	ds_read_b32 v11, v30 offset:460
	s_waitcnt lgkmcnt(0)
	v_mul_f32_e32 v8, 0x42800000, v8
	v_mul_f32_e32 v9, 0x42800000, v9
	v_med3_f32 v12, v8, s10, v46
	v_med3_f32 v9, v9, s10, v46
	v_mov_b32_e32 v8, v3
	v_cvt_pk_fp8_f32 v8, v12, v9
	v_mul_f32_e32 v10, 0x42800000, v10
	v_mul_f32_e32 v11, 0x42800000, v11
	v_med3_f32 v9, v10, s10, v46
	v_med3_f32 v10, v11, s10, v46
	v_cvt_pk_fp8_f32 v8, v9, v10 op_sel:[0,0,1]
	ds_read_b32 v9, v30 offset:592
	ds_read_b32 v10, v30 offset:724
	ds_read_b32 v11, v30 offset:856
	ds_read_b32 v12, v30 offset:988
	s_waitcnt lgkmcnt(0)
	v_mul_f32_e32 v9, 0x42800000, v9
	v_mul_f32_e32 v10, 0x42800000, v10
	v_med3_f32 v13, v9, s10, v46
	v_med3_f32 v10, v10, s10, v46
	v_mov_b32_e32 v9, v3
	v_cvt_pk_fp8_f32 v9, v13, v10
	v_mul_f32_e32 v11, 0x42800000, v11
	v_mul_f32_e32 v12, 0x42800000, v12
	v_med3_f32 v10, v11, s10, v46
	v_med3_f32 v11, v12, s10, v46
	v_cvt_pk_fp8_f32 v9, v10, v11 op_sel:[0,0,1]
	v_or_b32_e32 v10, s12, v28
	v_ashrrev_i32_e32 v11, 31, v10
	v_lshlrev_b64 v[10:11], 10, v[10:11]
	v_lshl_add_u64 v[10:11], v[6:7], 0, v[10:11]
	global_store_dwordx2 v[10:11], v[8:9], off nt
	ds_read_b32 v8, v30 offset:96
	ds_read_b32 v9, v30 offset:228
	ds_read_b32 v10, v30 offset:360
	ds_read_b32 v11, v30 offset:492
	s_waitcnt lgkmcnt(0)
	v_mul_f32_e32 v8, 0x42800000, v8
	v_mul_f32_e32 v9, 0x42800000, v9
	v_med3_f32 v12, v8, s10, v46
	v_med3_f32 v9, v9, s10, v46
	v_mov_b32_e32 v8, v3
	v_cvt_pk_fp8_f32 v8, v12, v9
	v_mul_f32_e32 v10, 0x42800000, v10
	v_mul_f32_e32 v11, 0x42800000, v11
	v_med3_f32 v9, v10, s10, v46
	v_med3_f32 v10, v11, s10, v46
	v_cvt_pk_fp8_f32 v8, v9, v10 op_sel:[0,0,1]
	ds_read_b32 v9, v30 offset:624
	ds_read_b32 v10, v30 offset:756
	ds_read_b32 v11, v30 offset:888
	ds_read_b32 v12, v30 offset:1020
	s_waitcnt lgkmcnt(0)
	v_mul_f32_e32 v9, 0x42800000, v9
	v_mul_f32_e32 v10, 0x42800000, v10
	v_med3_f32 v13, v9, s10, v46
	v_med3_f32 v10, v10, s10, v46
	v_mov_b32_e32 v9, v3
	v_cvt_pk_fp8_f32 v9, v13, v10
	v_mul_f32_e32 v11, 0x42800000, v11
	v_mul_f32_e32 v12, 0x42800000, v12
	v_med3_f32 v10, v11, s10, v46
	v_med3_f32 v11, v12, s10, v46
	v_cvt_pk_fp8_f32 v9, v10, v11 op_sel:[0,0,1]
	v_or_b32_e32 v10, s12, v29
	v_ashrrev_i32_e32 v11, 31, v10
	v_lshlrev_b64 v[10:11], 10, v[10:11]
	v_lshl_add_u64 v[6:7], v[6:7], 0, v[10:11]
	global_store_dwordx2 v[6:7], v[8:9], off nt
	s_waitcnt lgkmcnt(0)
	s_branch .LBB0_1443

.LBB0_2183:
	s_mul_hi_i32 s0, s21, 0x2aaaaaab
	s_lshr_b32 s1, s0, 31
	s_ashr_i32 s0, s0, 8
	s_add_i32 s12, s0, s1
	s_mul_i32 s0, s12, 0xfffffa00
	s_add_i32 s24, s21, s0
	s_lshr_b32 s0, s24, 22
	s_and_b32 s0, s0, 0x1ff
	s_add_i32 s25, s24, s0
	s_and_b32 s0, s25, 0xfe00
	s_sub_i32 s0, s24, s0
	s_sext_i32_i16 s1, s0
	s_bfe_u32 s1, s1, 0x5001a
	s_add_i32 s1, s0, s1
	s_sext_i32_i16 s10, s1
	s_and_b32 s1, s1, 0xffe0
	s_lshl_b32 s23, s10, 1
	s_sub_i32 s0, s0, s1
	s_andn2_b32 s23, s23, 63
	s_sext_i32_i16 s22, s0
	s_lshl_b32 s10, s22, 5
	v_or_b32_e32 v20, s23, v26
	s_mov_b64 s[14:15], -1
	s_cmpk_gt_i32 s24, 0x3ff
	v_ashrrev_i32_e32 v21, 31, v20
	v_or_b32_e32 v18, 8, v20
	v_or_b32_e32 v16, 16, v20
	v_or_b32_e32 v14, 24, v20
	v_or_b32_e32 v12, 32, v20
	v_or_b32_e32 v10, 40, v20
	v_or_b32_e32 v8, 48, v20
	v_or_b32_e32 v6, 56, v20
	s_cbranch_scc0 .LBB0_2185
	s_ashr_i32 s13, s12, 31
	s_lshl_b64 s[0:1], s[12:13], 20
	s_lshl_b64 s[14:15], s[12:13], 22
	s_add_u32 s13, s8, s14
	s_addc_u32 s14, s9, s15
	s_add_u32 s15, s6, s0
	s_addc_u32 s26, s7, s1
	s_ashr_i32 s11, s10, 31
	s_lshl_b64 s[0:1], s[10:11], 2
	s_add_u32 s0, s13, s0
	s_addc_u32 s1, s14, s1
	v_lshl_add_u64 v[72:73], s[0:1], 0, v[2:3]
	v_lshlrev_b64 v[22:23], 12, v[20:21]
	v_lshl_add_u64 v[22:23], v[72:73], 0, v[22:23]
	v_ashrrev_i32_e32 v19, 31, v18
	global_load_dwordx4 v[22:25], v[22:23], off nt
	v_lshlrev_b64 v[48:49], 12, v[18:19]
	v_lshl_add_u64 v[48:49], v[72:73], 0, v[48:49]
	v_ashrrev_i32_e32 v17, 31, v16
	global_load_dwordx4 v[48:51], v[48:49], off nt
	v_lshlrev_b64 v[52:53], 12, v[16:17]
	v_lshl_add_u64 v[52:53], v[72:73], 0, v[52:53]
	v_ashrrev_i32_e32 v15, 31, v14
	global_load_dwordx4 v[52:55], v[52:53], off nt
	v_lshlrev_b64 v[56:57], 12, v[14:15]
	v_lshl_add_u64 v[56:57], v[72:73], 0, v[56:57]
	v_ashrrev_i32_e32 v13, 31, v12
	global_load_dwordx4 v[56:59], v[56:57], off nt
	v_lshlrev_b64 v[60:61], 12, v[12:13]
	v_lshl_add_u64 v[60:61], v[72:73], 0, v[60:61]
	v_ashrrev_i32_e32 v11, 31, v10
	global_load_dwordx4 v[60:63], v[60:61], off nt
	v_lshlrev_b64 v[64:65], 12, v[10:11]
	v_lshl_add_u64 v[64:65], v[72:73], 0, v[64:65]
	v_ashrrev_i32_e32 v9, 31, v8
	global_load_dwordx4 v[64:67], v[64:65], off nt
	v_lshlrev_b64 v[68:69], 12, v[8:9]
	v_lshl_add_u64 v[68:69], v[72:73], 0, v[68:69]
	v_ashrrev_i32_e32 v7, 31, v6
	global_load_dwordx4 v[68:71], v[68:69], off nt
	v_lshlrev_b64 v[74:75], 12, v[6:7]
	v_lshl_add_u64 v[72:73], v[72:73], 0, v[74:75]
	global_load_dwordx4 v[72:75], v[72:73], off nt
	s_ashr_i32 s1, s23, 31
	s_add_u32 s0, s15, s23
	s_addc_u32 s1, s26, s1
	s_waitcnt vmcnt(0)
	ds_write2_b32 v31, v22, v23 offset1:1
	ds_write2_b32 v31, v24, v25 offset0:2 offset1:3
	s_waitcnt vmcnt(6)
	ds_write2_b32 v32, v48, v49 offset1:1
	ds_write2_b32 v33, v50, v51 offset1:1
	s_waitcnt vmcnt(5)
	ds_write2_b32 v34, v52, v53 offset1:1
	ds_write2_b32 v35, v54, v55 offset1:1
	s_waitcnt vmcnt(4)
	ds_write2_b32 v36, v56, v57 offset1:1
	ds_write2_b32 v37, v58, v59 offset1:1
	s_waitcnt vmcnt(3)
	ds_write2_b32 v38, v60, v61 offset1:1
	ds_write2_b32 v39, v62, v63 offset1:1
	s_waitcnt vmcnt(2)
	ds_write2_b32 v40, v64, v65 offset1:1
	ds_write2_b32 v41, v66, v67 offset1:1
	s_waitcnt vmcnt(1)
	ds_write2_b32 v42, v68, v69 offset1:1
	ds_write2_b32 v43, v70, v71 offset1:1
	s_waitcnt vmcnt(0)
	ds_write2_b32 v44, v72, v73 offset1:1
	ds_write2_b32 v45, v74, v75 offset1:1
	s_waitcnt lgkmcnt(0)
	ds_read_b32 v7, v30
	ds_read_b32 v9, v30 offset:132
	ds_read_b32 v11, v30 offset:264
	ds_read_b32 v13, v30 offset:396
	v_mov_b32_e32 v24, v3
	s_waitcnt lgkmcnt(0)
	v_mul_f32_e32 v7, 0x43000000, v7
	s_waitcnt lgkmcnt(2)
	v_mul_f32_e32 v9, 0x43000000, v9
	v_med3_f32 v7, v7, s20, v46
	v_med3_f32 v9, v9, s20, v46
	v_cvt_pk_fp8_f32 v24, v7, v9
	s_waitcnt lgkmcnt(1)
	v_mul_f32_e32 v11, 0x43000000, v11
	s_waitcnt lgkmcnt(0)
	v_mul_f32_e32 v13, 0x43000000, v13
	v_med3_f32 v7, v11, s20, v46
	v_med3_f32 v9, v13, s20, v46
	v_cvt_pk_fp8_f32 v24, v7, v9 op_sel:[0,0,1]
	ds_read_b32 v7, v30 offset:528
	ds_read_b32 v9, v30 offset:660
	ds_read_b32 v11, v30 offset:792
	ds_read_b32 v13, v30 offset:924
	v_mov_b32_e32 v25, v3
	s_waitcnt lgkmcnt(3)
	v_mul_f32_e32 v7, 0x43000000, v7
	s_waitcnt lgkmcnt(2)
	v_mul_f32_e32 v9, 0x43000000, v9
	v_med3_f32 v7, v7, s20, v46
	v_med3_f32 v9, v9, s20, v46
	v_cvt_pk_fp8_f32 v25, v7, v9
	s_waitcnt lgkmcnt(1)
	v_mul_f32_e32 v11, 0x43000000, v11
	s_waitcnt lgkmcnt(0)
	v_mul_f32_e32 v13, 0x43000000, v13
	v_med3_f32 v7, v11, s20, v46
	v_med3_f32 v9, v13, s20, v46
	v_cvt_pk_fp8_f32 v25, v7, v9 op_sel:[0,0,1]
	v_or_b32_e32 v48, s10, v26
	v_ashrrev_i32_e32 v49, 31, v48
	v_lshl_add_u64 v[22:23], s[0:1], 0, v[4:5]
	v_lshlrev_b64 v[48:49], 10, v[48:49]
	v_lshl_add_u64 v[48:49], v[22:23], 0, v[48:49]
	global_store_dwordx2 v[48:49], v[24:25], off nt
	ds_read_b32 v7, v30 offset:32
	ds_read_b32 v9, v30 offset:164
	ds_read_b32 v11, v30 offset:296
	ds_read_b32 v13, v30 offset:428
	v_mov_b32_e32 v24, v3
	s_waitcnt lgkmcnt(0)
	v_mul_f32_e32 v7, 0x43000000, v7
	v_mul_f32_e32 v9, 0x43000000, v9
	v_med3_f32 v7, v7, s20, v46
	v_med3_f32 v9, v9, s20, v46
	v_cvt_pk_fp8_f32 v24, v7, v9
	v_mul_f32_e32 v11, 0x43000000, v11
	v_mul_f32_e32 v13, 0x43000000, v13
	v_med3_f32 v7, v11, s20, v46
	v_med3_f32 v9, v13, s20, v46
	v_cvt_pk_fp8_f32 v24, v7, v9 op_sel:[0,0,1]
	ds_read_b32 v7, v30 offset:560
	ds_read_b32 v9, v30 offset:692
	ds_read_b32 v11, v30 offset:824
	ds_read_b32 v13, v30 offset:956
	v_mov_b32_e32 v25, v3
	s_waitcnt lgkmcnt(0)
	v_mul_f32_e32 v7, 0x43000000, v7
	v_mul_f32_e32 v9, 0x43000000, v9
	v_med3_f32 v7, v7, s20, v46
	v_med3_f32 v9, v9, s20, v46
	v_cvt_pk_fp8_f32 v25, v7, v9
	v_mul_f32_e32 v11, 0x43000000, v11
	v_mul_f32_e32 v13, 0x43000000, v13
	v_med3_f32 v7, v11, s20, v46
	v_med3_f32 v9, v13, s20, v46
	v_cvt_pk_fp8_f32 v25, v7, v9 op_sel:[0,0,1]
	v_or_b32_e32 v48, s10, v27
	v_ashrrev_i32_e32 v49, 31, v48
	v_lshlrev_b64 v[48:49], 10, v[48:49]
	v_lshl_add_u64 v[48:49], v[22:23], 0, v[48:49]
	global_store_dwordx2 v[48:49], v[24:25], off nt
	ds_read_b32 v7, v30 offset:64
	ds_read_b32 v9, v30 offset:196
	ds_read_b32 v11, v30 offset:328
	ds_read_b32 v13, v30 offset:460
	v_mov_b32_e32 v24, v3
	s_waitcnt lgkmcnt(0)
	v_mul_f32_e32 v7, 0x43000000, v7
	v_mul_f32_e32 v9, 0x43000000, v9
	v_med3_f32 v7, v7, s20, v46
	v_med3_f32 v9, v9, s20, v46
	v_cvt_pk_fp8_f32 v24, v7, v9
	v_mul_f32_e32 v11, 0x43000000, v11
	v_mul_f32_e32 v13, 0x43000000, v13
	v_med3_f32 v7, v11, s20, v46
	v_med3_f32 v9, v13, s20, v46
	v_cvt_pk_fp8_f32 v24, v7, v9 op_sel:[0,0,1]
	ds_read_b32 v7, v30 offset:592
	ds_read_b32 v9, v30 offset:724
	ds_read_b32 v11, v30 offset:856
	ds_read_b32 v13, v30 offset:988
	v_mov_b32_e32 v25, v3
	s_waitcnt lgkmcnt(0)
	v_mul_f32_e32 v7, 0x43000000, v7
	v_mul_f32_e32 v9, 0x43000000, v9
	v_med3_f32 v7, v7, s20, v46
	v_med3_f32 v9, v9, s20, v46
	v_cvt_pk_fp8_f32 v25, v7, v9
	v_mul_f32_e32 v11, 0x43000000, v11
	v_mul_f32_e32 v13, 0x43000000, v13
	v_med3_f32 v7, v11, s20, v46
	v_med3_f32 v9, v13, s20, v46
	v_cvt_pk_fp8_f32 v25, v7, v9 op_sel:[0,0,1]
	v_or_b32_e32 v48, s10, v28
	v_ashrrev_i32_e32 v49, 31, v48
	v_lshlrev_b64 v[48:49], 10, v[48:49]
	v_lshl_add_u64 v[48:49], v[22:23], 0, v[48:49]
	global_store_dwordx2 v[48:49], v[24:25], off nt
	ds_read_b32 v7, v30 offset:96
	ds_read_b32 v9, v30 offset:228
	ds_read_b32 v11, v30 offset:360
	ds_read_b32 v13, v30 offset:492
	v_mov_b32_e32 v24, v3
	s_waitcnt lgkmcnt(0)
	v_mul_f32_e32 v7, 0x43000000, v7
	v_mul_f32_e32 v9, 0x43000000, v9
	v_med3_f32 v7, v7, s20, v46
	v_med3_f32 v9, v9, s20, v46
	v_cvt_pk_fp8_f32 v24, v7, v9
	v_mul_f32_e32 v11, 0x43000000, v11
	v_mul_f32_e32 v13, 0x43000000, v13
	v_med3_f32 v7, v11, s20, v46
	v_med3_f32 v9, v13, s20, v46
	v_cvt_pk_fp8_f32 v24, v7, v9 op_sel:[0,0,1]
	ds_read_b32 v7, v30 offset:624
	ds_read_b32 v9, v30 offset:756
	ds_read_b32 v11, v30 offset:888
	ds_read_b32 v13, v30 offset:1020
	v_mov_b32_e32 v25, v3
	s_waitcnt lgkmcnt(0)
	v_mul_f32_e32 v7, 0x43000000, v7
	v_mul_f32_e32 v9, 0x43000000, v9
	v_med3_f32 v7, v7, s20, v46
	v_med3_f32 v9, v9, s20, v46
	v_cvt_pk_fp8_f32 v25, v7, v9
	v_mul_f32_e32 v11, 0x43000000, v11
	v_mul_f32_e32 v13, 0x43000000, v13
	v_med3_f32 v7, v11, s20, v46
	v_med3_f32 v9, v13, s20, v46
	v_cvt_pk_fp8_f32 v25, v7, v9 op_sel:[0,0,1]
	v_or_b32_e32 v48, s10, v29
	v_ashrrev_i32_e32 v49, 31, v48
	v_lshlrev_b64 v[48:49], 10, v[48:49]
	v_lshl_add_u64 v[22:23], v[22:23], 0, v[48:49]
	global_store_dwordx2 v[22:23], v[24:25], off nt
	s_waitcnt lgkmcnt(0)
	s_cbranch_execnz .LBB0_2182
	s_branch .LBB0_2186

.LBB0_2186:
	s_sext_i32_i16 s0, s25
	s_lshr_b32 s0, s0, 9
	s_addk_i32 s24, 0x1ff
	s_cmpk_lt_u32 s24, 0x3ff
	s_cselect_b32 s11, s17, s19
	s_cselect_b32 s15, s16, s18
	s_ashr_i32 s13, s12, 31
	s_sext_i32_i16 s14, s0
	s_lshl_b64 s[0:1], s[12:13], 22
	s_add_u32 s15, s15, s0
	s_addc_u32 s24, s11, s1
	s_lshl_b64 s[0:1], s[12:13], 21
	s_add_u32 s12, s4, s0
	s_addc_u32 s13, s5, s1
	s_ashr_i32 s11, s10, 31
	s_lshl_b64 s[0:1], s[10:11], 2
	s_add_u32 s0, s15, s0
	s_addc_u32 s1, s24, s1
	v_lshl_add_u64 v[22:23], s[0:1], 0, v[2:3]
	s_mov_b64 s[0:1], 0xc000000
	v_lshl_add_u64 v[24:25], v[22:23], 0, s[0:1]
	v_lshlrev_b64 v[20:21], 12, v[20:21]
	v_lshl_add_u64 v[20:21], v[24:25], 0, v[20:21]
	v_ashrrev_i32_e32 v19, 31, v18
	global_load_dwordx4 v[20:23], v[20:21], off nt
	v_lshlrev_b64 v[18:19], 12, v[18:19]
	v_lshl_add_u64 v[18:19], v[24:25], 0, v[18:19]
	v_ashrrev_i32_e32 v17, 31, v16
	global_load_dwordx4 v[48:51], v[18:19], off nt
	v_lshlrev_b64 v[16:17], 12, v[16:17]
	v_lshl_add_u64 v[16:17], v[24:25], 0, v[16:17]
	v_ashrrev_i32_e32 v15, 31, v14
	global_load_dwordx4 v[16:19], v[16:17], off nt
	v_lshlrev_b64 v[14:15], 12, v[14:15]
	v_lshl_add_u64 v[14:15], v[24:25], 0, v[14:15]
	v_ashrrev_i32_e32 v13, 31, v12
	global_load_dwordx4 v[52:55], v[14:15], off nt
	v_lshlrev_b64 v[12:13], 12, v[12:13]
	v_lshl_add_u64 v[12:13], v[24:25], 0, v[12:13]
	v_ashrrev_i32_e32 v11, 31, v10
	global_load_dwordx4 v[12:15], v[12:13], off nt
	v_lshlrev_b64 v[10:11], 12, v[10:11]
	v_lshl_add_u64 v[10:11], v[24:25], 0, v[10:11]
	v_ashrrev_i32_e32 v9, 31, v8
	global_load_dwordx4 v[56:59], v[10:11], off nt
	v_lshlrev_b64 v[8:9], 12, v[8:9]
	v_lshl_add_u64 v[8:9], v[24:25], 0, v[8:9]
	v_ashrrev_i32_e32 v7, 31, v6
	global_load_dwordx4 v[8:11], v[8:9], off nt
	v_lshlrev_b64 v[6:7], 12, v[6:7]
	v_lshl_add_u64 v[6:7], v[24:25], 0, v[6:7]
	global_load_dwordx4 v[60:63], v[6:7], off nt
	s_lshl_b32 s1, s14, 7
	s_ashr_i32 s0, s23, 31
	s_add_u32 s12, s12, s23
	s_addc_u32 s13, s13, s0
	s_lshl_b32 s0, s22, 6
	s_and_b32 s0, s0, 0xffffff00
	s_add_i32 s0, s0, s1
	s_and_b32 s1, s10, 0x60
	s_or_b32 s10, s0, s1
	v_lshl_add_u64 v[6:7], s[12:13], 0, v[4:5]
	s_waitcnt vmcnt(0)
	ds_write2_b32 v31, v20, v21 offset1:1
	ds_write2_b32 v31, v22, v23 offset0:2 offset1:3
	ds_write2_b32 v32, v48, v49 offset1:1
	ds_write2_b32 v33, v50, v51 offset1:1
	ds_write2_b32 v34, v16, v17 offset1:1
	ds_write2_b32 v35, v18, v19 offset1:1
	ds_write2_b32 v36, v52, v53 offset1:1
	ds_write2_b32 v37, v54, v55 offset1:1
	ds_write2_b32 v38, v12, v13 offset1:1
	ds_write2_b32 v39, v14, v15 offset1:1
	ds_write2_b32 v40, v56, v57 offset1:1
	ds_write2_b32 v41, v58, v59 offset1:1
	ds_write2_b32 v42, v8, v9 offset1:1
	ds_write2_b32 v43, v10, v11 offset1:1
	ds_write2_b32 v44, v60, v61 offset1:1
	ds_write2_b32 v45, v62, v63 offset1:1
	s_waitcnt lgkmcnt(0)
	ds_read_b32 v8, v30
	ds_read_b32 v9, v30 offset:132
	ds_read_b32 v10, v30 offset:264
	ds_read_b32 v11, v30 offset:396
	s_waitcnt lgkmcnt(0)
	v_mul_f32_e32 v8, 0x42800000, v8
	v_mul_f32_e32 v9, 0x42800000, v9
	v_med3_f32 v12, v8, s20, v46
	v_med3_f32 v9, v9, s20, v46
	v_mov_b32_e32 v8, v3
	v_cvt_pk_fp8_f32 v8, v12, v9
	v_mul_f32_e32 v10, 0x42800000, v10
	v_mul_f32_e32 v11, 0x42800000, v11
	v_med3_f32 v9, v10, s20, v46
	v_med3_f32 v10, v11, s20, v46
	v_cvt_pk_fp8_f32 v8, v9, v10 op_sel:[0,0,1]
	ds_read_b32 v9, v30 offset:528
	ds_read_b32 v10, v30 offset:660
	ds_read_b32 v11, v30 offset:792
	ds_read_b32 v12, v30 offset:924
	s_waitcnt lgkmcnt(3)
	v_mul_f32_e32 v9, 0x42800000, v9
	s_waitcnt lgkmcnt(2)
	v_mul_f32_e32 v10, 0x42800000, v10
	v_med3_f32 v13, v9, s20, v46
	v_med3_f32 v10, v10, s20, v46
	v_mov_b32_e32 v9, v3
	v_cvt_pk_fp8_f32 v9, v13, v10
	s_waitcnt lgkmcnt(1)
	v_mul_f32_e32 v11, 0x42800000, v11
	s_waitcnt lgkmcnt(0)
	v_mul_f32_e32 v12, 0x42800000, v12
	v_med3_f32 v10, v11, s20, v46
	v_med3_f32 v11, v12, s20, v46
	v_cvt_pk_fp8_f32 v9, v10, v11 op_sel:[0,0,1]
	v_or_b32_e32 v10, s10, v26
	v_ashrrev_i32_e32 v11, 31, v10
	v_lshlrev_b64 v[10:11], 10, v[10:11]
	v_lshl_add_u64 v[10:11], v[6:7], 0, v[10:11]
	global_store_dwordx2 v[10:11], v[8:9], off nt
	ds_read_b32 v8, v30 offset:32
	ds_read_b32 v9, v30 offset:164
	ds_read_b32 v10, v30 offset:296
	ds_read_b32 v11, v30 offset:428
	s_waitcnt lgkmcnt(0)
	v_mul_f32_e32 v8, 0x42800000, v8
	v_mul_f32_e32 v9, 0x42800000, v9
	v_med3_f32 v12, v8, s20, v46
	v_med3_f32 v9, v9, s20, v46
	v_mov_b32_e32 v8, v3
	v_cvt_pk_fp8_f32 v8, v12, v9
	v_mul_f32_e32 v10, 0x42800000, v10
	v_mul_f32_e32 v11, 0x42800000, v11
	v_med3_f32 v9, v10, s20, v46
	v_med3_f32 v10, v11, s20, v46
	v_cvt_pk_fp8_f32 v8, v9, v10 op_sel:[0,0,1]
	ds_read_b32 v9, v30 offset:560
	ds_read_b32 v10, v30 offset:692
	ds_read_b32 v11, v30 offset:824
	ds_read_b32 v12, v30 offset:956
	s_waitcnt lgkmcnt(0)
	v_mul_f32_e32 v9, 0x42800000, v9
	v_mul_f32_e32 v10, 0x42800000, v10
	v_med3_f32 v13, v9, s20, v46
	v_med3_f32 v10, v10, s20, v46
	v_mov_b32_e32 v9, v3
	v_cvt_pk_fp8_f32 v9, v13, v10
	v_mul_f32_e32 v11, 0x42800000, v11
	v_mul_f32_e32 v12, 0x42800000, v12
	v_med3_f32 v10, v11, s20, v46
	v_med3_f32 v11, v12, s20, v46
	v_cvt_pk_fp8_f32 v9, v10, v11 op_sel:[0,0,1]
	v_or_b32_e32 v10, s10, v27
	v_ashrrev_i32_e32 v11, 31, v10
	v_lshlrev_b64 v[10:11], 10, v[10:11]
	v_lshl_add_u64 v[10:11], v[6:7], 0, v[10:11]
	global_store_dwordx2 v[10:11], v[8:9], off nt
	ds_read_b32 v8, v30 offset:64
	ds_read_b32 v9, v30 offset:196
	ds_read_b32 v10, v30 offset:328
	ds_read_b32 v11, v30 offset:460
	s_waitcnt lgkmcnt(0)
	v_mul_f32_e32 v8, 0x42800000, v8
	v_mul_f32_e32 v9, 0x42800000, v9
	v_med3_f32 v12, v8, s20, v46
	v_med3_f32 v9, v9, s20, v46
	v_mov_b32_e32 v8, v3
	v_cvt_pk_fp8_f32 v8, v12, v9
	v_mul_f32_e32 v10, 0x42800000, v10
	v_mul_f32_e32 v11, 0x42800000, v11
	v_med3_f32 v9, v10, s20, v46
	v_med3_f32 v10, v11, s20, v46
	v_cvt_pk_fp8_f32 v8, v9, v10 op_sel:[0,0,1]
	ds_read_b32 v9, v30 offset:592
	ds_read_b32 v10, v30 offset:724
	ds_read_b32 v11, v30 offset:856
	ds_read_b32 v12, v30 offset:988
	s_waitcnt lgkmcnt(0)
	v_mul_f32_e32 v9, 0x42800000, v9
	v_mul_f32_e32 v10, 0x42800000, v10
	v_med3_f32 v13, v9, s20, v46
	v_med3_f32 v10, v10, s20, v46
	v_mov_b32_e32 v9, v3
	v_cvt_pk_fp8_f32 v9, v13, v10
	v_mul_f32_e32 v11, 0x42800000, v11
	v_mul_f32_e32 v12, 0x42800000, v12
	v_med3_f32 v10, v11, s20, v46
	v_med3_f32 v11, v12, s20, v46
	v_cvt_pk_fp8_f32 v9, v10, v11 op_sel:[0,0,1]
	v_or_b32_e32 v10, s10, v28
	v_ashrrev_i32_e32 v11, 31, v10
	v_lshlrev_b64 v[10:11], 10, v[10:11]
	v_lshl_add_u64 v[10:11], v[6:7], 0, v[10:11]
	global_store_dwordx2 v[10:11], v[8:9], off nt
	ds_read_b32 v8, v30 offset:96
	ds_read_b32 v9, v30 offset:228
	ds_read_b32 v10, v30 offset:360
	ds_read_b32 v11, v30 offset:492
	s_waitcnt lgkmcnt(0)
	v_mul_f32_e32 v8, 0x42800000, v8
	v_mul_f32_e32 v9, 0x42800000, v9
	v_med3_f32 v12, v8, s20, v46
	v_med3_f32 v9, v9, s20, v46
	v_mov_b32_e32 v8, v3
	v_cvt_pk_fp8_f32 v8, v12, v9
	v_mul_f32_e32 v10, 0x42800000, v10
	v_mul_f32_e32 v11, 0x42800000, v11
	v_med3_f32 v9, v10, s20, v46
	v_med3_f32 v10, v11, s20, v46
	v_cvt_pk_fp8_f32 v8, v9, v10 op_sel:[0,0,1]
	ds_read_b32 v9, v30 offset:624
	ds_read_b32 v10, v30 offset:756
	ds_read_b32 v11, v30 offset:888
	ds_read_b32 v12, v30 offset:1020
	s_waitcnt lgkmcnt(0)
	v_mul_f32_e32 v9, 0x42800000, v9
	v_mul_f32_e32 v10, 0x42800000, v10
	v_med3_f32 v13, v9, s20, v46
	v_med3_f32 v10, v10, s20, v46
	v_mov_b32_e32 v9, v3
	v_cvt_pk_fp8_f32 v9, v13, v10
	v_mul_f32_e32 v11, 0x42800000, v11
	v_mul_f32_e32 v12, 0x42800000, v12
	v_med3_f32 v10, v11, s20, v46
	v_med3_f32 v11, v12, s20, v46
	v_cvt_pk_fp8_f32 v9, v10, v11 op_sel:[0,0,1]
	v_or_b32_e32 v10, s10, v29
	v_ashrrev_i32_e32 v11, 31, v10
	v_lshlrev_b64 v[10:11], 10, v[10:11]
	v_lshl_add_u64 v[6:7], v[6:7], 0, v[10:11]
	global_store_dwordx2 v[6:7], v[8:9], off nt
	s_waitcnt lgkmcnt(0)
	s_branch .LBB0_2182
